# sparse attention: running max folded into the QK accumulator start value; tiles inside the deferred-rescale window skip the per-element subtraction and rescale bookkeeping
# speedup vs baseline: 1.0099x; 1.0070x over previous
.Lsmg_4:
	v_exp_f32_e32 v66, v66
	v_exp_f32_e32 v67, v67
	v_exp_f32_e32 v82, v82
	v_exp_f32_e32 v83, v83
	v_exp_f32_e32 v68, v68
	v_exp_f32_e32 v69, v69
	v_exp_f32_e32 v84, v84
	v_exp_f32_e32 v85, v85
	v_pk_add_f32 v[100:101], v[66:67], v[82:83]
	v_exp_f32_e32 v70, v70
	v_exp_f32_e32 v71, v71
	v_exp_f32_e32 v86, v86
	v_exp_f32_e32 v87, v87
	v_pk_add_f32 v[100:101], v[100:101], v[68:69]
	v_pk_add_f32 v[100:101], v[100:101], v[84:85]
	v_exp_f32_e32 v72, v72
	v_exp_f32_e32 v73, v73
	v_exp_f32_e32 v88, v88
	v_exp_f32_e32 v89, v89
	v_pk_add_f32 v[100:101], v[100:101], v[70:71]
	v_pk_add_f32 v[100:101], v[100:101], v[86:87]
	v_exp_f32_e32 v74, v74
	v_exp_f32_e32 v75, v75
	v_exp_f32_e32 v90, v90
	v_exp_f32_e32 v91, v91
	v_pk_add_f32 v[100:101], v[100:101], v[72:73]
	v_pk_add_f32 v[100:101], v[100:101], v[88:89]
	v_exp_f32_e32 v76, v76
	v_exp_f32_e32 v77, v77
	v_exp_f32_e32 v92, v92
	v_exp_f32_e32 v93, v93
	v_pk_add_f32 v[100:101], v[100:101], v[74:75]
	v_pk_add_f32 v[100:101], v[100:101], v[90:91]
	v_exp_f32_e32 v78, v78
	v_exp_f32_e32 v79, v79
	v_exp_f32_e32 v94, v94
	v_exp_f32_e32 v95, v95
	v_pk_add_f32 v[100:101], v[100:101], v[76:77]
	v_pk_add_f32 v[100:101], v[100:101], v[92:93]
	v_exp_f32_e32 v80, v80
	v_exp_f32_e32 v81, v81
	v_exp_f32_e32 v96, v96
	v_exp_f32_e32 v97, v97
	v_pk_add_f32 v[100:101], v[100:101], v[78:79]
	v_pk_add_f32 v[100:101], v[100:101], v[94:95]
	s_nop 0
	v_pk_add_f32 v[100:101], v[100:101], v[80:81]
	v_pk_add_f32 v[100:101], v[100:101], v[96:97]
	v_add_f32_e32 v99, v100, v101
	s_branch .Lsmj_4

.Lsmj_4:
	s_mul_i32 s8, s48, 0x8c00
	v_fmac_f32_e32 v99, v193, v98
	v_add_u32_e32 v98, s8, v212
	v_cvt_pk_bf16_f32 v66, v66, v67
	v_cvt_pk_bf16_f32 v67, v68, v69
	v_cvt_pk_bf16_f32 v68, v70, v71
	v_cvt_pk_bf16_f32 v69, v72, v73
	v_cvt_pk_bf16_f32 v70, v74, v75
	v_cvt_pk_bf16_f32 v71, v76, v77
	v_cvt_pk_bf16_f32 v72, v78, v79
	v_cvt_pk_bf16_f32 v73, v80, v81
	v_cvt_pk_bf16_f32 v74, v82, v83
	v_cvt_pk_bf16_f32 v75, v84, v85
	v_cvt_pk_bf16_f32 v76, v86, v87
	v_cvt_pk_bf16_f32 v77, v88, v89
	v_cvt_pk_bf16_f32 v78, v90, v91
	v_cvt_pk_bf16_f32 v79, v92, v93
	v_cvt_pk_bf16_f32 v80, v94, v95
	v_cvt_pk_bf16_f32 v81, v96, v97
	ds_read_b128 v[82:85], v98 offset:17408
	ds_read_b128 v[86:89], v98 offset:22016
	ds_read_b128 v[90:93], v98 offset:26624
	ds_read_b128 v[94:97], v98 offset:31232
	s_setprio 1
	s_waitcnt lgkmcnt(3)
	v_mfma_f32_32x32x16_bf16 v[50:65], v[82:85], v[66:69], v[50:65]
	s_waitcnt lgkmcnt(2)
	v_mfma_f32_32x32x16_bf16 v[34:49], v[86:89], v[66:69], v[34:49]
	s_waitcnt lgkmcnt(1)
	v_mfma_f32_32x32x16_bf16 v[18:33], v[90:93], v[66:69], v[18:33]
	s_waitcnt lgkmcnt(0)
	v_mfma_f32_32x32x16_bf16 v[2:17], v[94:97], v[66:69], v[2:17]
	s_setprio 0
	ds_read_b128 v[66:69], v98 offset:17440
	ds_read_b128 v[82:85], v98 offset:22048
	ds_read_b128 v[86:89], v98 offset:26656
	ds_read_b128 v[90:93], v98 offset:31264
	s_setprio 1
	s_waitcnt lgkmcnt(3)
	v_mfma_f32_32x32x16_bf16 v[50:65], v[66:69], v[70:73], v[50:65]
	s_waitcnt lgkmcnt(2)
	v_mfma_f32_32x32x16_bf16 v[34:49], v[82:85], v[70:73], v[34:49]
	s_waitcnt lgkmcnt(1)
	v_mfma_f32_32x32x16_bf16 v[18:33], v[86:89], v[70:73], v[18:33]
	s_waitcnt lgkmcnt(0)
	v_mfma_f32_32x32x16_bf16 v[2:17], v[90:93], v[70:73], v[2:17]
	s_setprio 0
	ds_read_b128 v[66:69], v98 offset:17472
	ds_read_b128 v[70:73], v98 offset:22080
	ds_read_b128 v[82:85], v98 offset:26688
	ds_read_b128 v[86:89], v98 offset:31296
	s_setprio 1
	s_waitcnt lgkmcnt(3)
	v_mfma_f32_32x32x16_bf16 v[50:65], v[66:69], v[74:77], v[50:65]
	s_waitcnt lgkmcnt(2)
	v_mfma_f32_32x32x16_bf16 v[34:49], v[70:73], v[74:77], v[34:49]
	s_waitcnt lgkmcnt(1)
	v_mfma_f32_32x32x16_bf16 v[18:33], v[82:85], v[74:77], v[18:33]
	s_waitcnt lgkmcnt(0)
	v_mfma_f32_32x32x16_bf16 v[2:17], v[86:89], v[74:77], v[2:17]
	s_setprio 0
	ds_read_b128 v[66:69], v98 offset:17504
	ds_read_b128 v[70:73], v98 offset:22112
	ds_read_b128 v[74:77], v98 offset:26720
	ds_read_b128 v[82:85], v98 offset:31328
	s_setprio 1
	s_waitcnt lgkmcnt(3)
	v_mfma_f32_32x32x16_bf16 v[50:65], v[66:69], v[78:81], v[50:65]
	s_waitcnt lgkmcnt(2)
	v_mfma_f32_32x32x16_bf16 v[34:49], v[70:73], v[78:81], v[34:49]
	s_waitcnt lgkmcnt(1)
	v_mfma_f32_32x32x16_bf16 v[18:33], v[74:77], v[78:81], v[18:33]
	s_waitcnt lgkmcnt(0)
	v_mfma_f32_32x32x16_bf16 v[2:17], v[82:85], v[78:81], v[2:17]
	s_setprio 0
	v_mov_b32_e32 v193, v99

.LBB0_60:
	s_lshl_b64 s[28:29], s[0:1], 11
	s_and_b32 s0, s45, 3
	s_lshl_b32 s1, s0, 23
	s_lshl_b32 s45, s0, 8
	s_add_u32 s0, s8, s1
	s_addc_u32 s1, s9, 0
	v_lshl_add_u64 v[198:199], s[0:1], 0, v[188:189]
	s_add_u32 s0, s45, s30
	v_mov_b32_e32 v50, v1
	v_mov_b32_e32 v51, v1
	v_lshl_add_u64 v[196:197], v[2:3], 0, 8
	s_addc_u32 s1, 0, s31
	v_mov_b32_e32 v52, v1
	v_mov_b32_e32 v53, v1
	v_mov_b32_e32 v54, v1
	v_mov_b32_e32 v55, v1
	v_mov_b32_e32 v56, v1
	v_mov_b32_e32 v57, v1
	v_mov_b32_e32 v58, v1
	v_mov_b32_e32 v59, v1
	v_mov_b32_e32 v60, v1
	v_mov_b32_e32 v61, v1
	v_mov_b32_e32 v62, v1
	v_mov_b32_e32 v63, v1
	v_mov_b32_e32 v64, v1
	v_mov_b32_e32 v65, v1
	v_mov_b32_e32 v193, 0
	v_mov_b64_e32 v[34:35], v[50:51]
	v_mov_b64_e32 v[18:19], v[50:51]
	v_mov_b64_e32 v[2:3], v[50:51]
	s_mov_b32 s44, 3
	s_waitcnt lgkmcnt(0)
	s_barrier
	v_lshl_add_u64 v[200:201], s[0:1], 0, v[190:191]
	s_mov_b32 s49, 0
	s_mov_b32 s45, 1
	s_mov_b32 s48, 2
	v_mov_b32_e32 v195, 0xff800000
	v_mov_b32_e32 v230, 0
	v_mov_b32_e32 v245, v231
	v_mov_b64_e32 v[36:37], v[52:53]
	v_mov_b64_e32 v[38:39], v[54:55]
	v_mov_b64_e32 v[40:41], v[56:57]
	v_mov_b64_e32 v[42:43], v[58:59]
	v_mov_b64_e32 v[44:45], v[60:61]
	v_mov_b64_e32 v[46:47], v[62:63]
	v_mov_b64_e32 v[48:49], v[64:65]
	v_mov_b64_e32 v[20:21], v[52:53]
	v_mov_b64_e32 v[22:23], v[54:55]
	v_mov_b64_e32 v[24:25], v[56:57]
	v_mov_b64_e32 v[26:27], v[58:59]
	v_mov_b64_e32 v[28:29], v[60:61]
	v_mov_b64_e32 v[30:31], v[62:63]
	v_mov_b64_e32 v[32:33], v[64:65]
	v_mov_b64_e32 v[4:5], v[52:53]
	v_mov_b64_e32 v[6:7], v[54:55]
	v_mov_b64_e32 v[8:9], v[56:57]
	v_mov_b64_e32 v[10:11], v[58:59]
	v_mov_b64_e32 v[12:13], v[60:61]
	v_mov_b64_e32 v[14:15], v[62:63]
	v_mov_b64_e32 v[16:17], v[64:65]
	v_mov_b32_e32 v82, 0
	v_mov_b32_e32 v83, v193
	v_mov_b32_e32 v84, v193
	v_mov_b32_e32 v85, v193
	v_mov_b32_e32 v86, v193
	v_mov_b32_e32 v87, v193
	v_mov_b32_e32 v88, v193
	v_mov_b32_e32 v89, v193
	v_mov_b32_e32 v90, v193
	v_mov_b32_e32 v91, v193
	v_mov_b32_e32 v92, v193
	v_mov_b32_e32 v93, v193
	v_mov_b32_e32 v94, v193
	v_mov_b32_e32 v95, v193
	v_mov_b32_e32 v96, v193
	v_mov_b32_e32 v97, v193
	v_mov_b32_e32 v66, 0
	v_mov_b32_e32 v67, v193
	v_mov_b32_e32 v68, v193
	v_mov_b32_e32 v69, v193
	v_mov_b32_e32 v70, v193
	v_mov_b32_e32 v71, v193
	v_mov_b32_e32 v72, v193
	v_mov_b32_e32 v73, v193
	v_mov_b32_e32 v74, v193
	v_mov_b32_e32 v75, v193
	v_mov_b32_e32 v76, v193
	v_mov_b32_e32 v77, v193
	v_mov_b32_e32 v78, v193
	v_mov_b32_e32 v79, v193
	v_mov_b32_e32 v80, v193
	v_mov_b32_e32 v81, v193
	s_branch .LBB0_63

.LBB0_67:
	s_mul_i32 s0, s49, 0x8c00
	s_add_i32 s47, s0, 0
	v_add3_u32 v217, s47, v209, v210
	v_lshrrev_b32_e32 v218, v186, v202
	v_lshrrev_b32_e32 v203, v186, v203
	s_and_saveexec_b64 s[0:1], s[6:7]
	s_xor_b64 s[0:1], exec, s[0:1]
	s_cbranch_execz .LBB0_71
	v_not_b32_e32 v66, v218
	v_not_b32_e32 v82, v203
	v_bfe_i32 v83, v66, 0, 1
	v_bfe_i32 v174, v82, 0, 1
	v_bfe_i32 v67, v66, 1, 1
	v_bfe_i32 v175, v82, 1, 1
	v_bfe_i32 v68, v66, 2, 1
	v_bfe_i32 v84, v82, 2, 1
	v_bfe_i32 v69, v66, 3, 1
	v_bfe_i32 v85, v82, 3, 1
	v_bfe_i32 v70, v66, 8, 1
	v_bfe_i32 v86, v82, 8, 1
	v_bfe_i32 v71, v66, 9, 1
	v_bfe_i32 v87, v82, 9, 1
	v_bfe_i32 v72, v66, 10, 1
	v_bfe_i32 v88, v82, 10, 1
	v_bfe_i32 v73, v66, 11, 1
	v_bfe_i32 v89, v82, 11, 1
	v_bfe_i32 v74, v66, 16, 1
	v_bfe_i32 v90, v82, 16, 1
	v_bfe_i32 v75, v66, 17, 1
	v_bfe_i32 v91, v82, 17, 1
	v_bfe_i32 v76, v66, 18, 1
	v_bfe_i32 v92, v82, 18, 1
	v_bfe_i32 v77, v66, 19, 1
	v_bfe_i32 v93, v82, 19, 1
	v_bfe_i32 v78, v66, 24, 1
	v_bfe_i32 v94, v82, 24, 1
	v_bfe_i32 v79, v66, 25, 1
	v_bfe_i32 v95, v82, 25, 1
	v_bfe_i32 v80, v66, 26, 1
	v_bfe_i32 v96, v82, 26, 1
	v_bfe_i32 v66, v66, 27, 1
	v_bfe_i32 v82, v82, 27, 1
	s_nop 0
	v_bfi_b32 v79, v79, v231, v230
	v_bfi_b32 v81, v66, v231, v230
	v_bfi_b32 v66, v83, v231, v230
	v_bfi_b32 v97, v82, v231, v230
	v_bfi_b32 v83, v175, v231, v230
	v_bfi_b32 v82, v174, v231, v230
	ds_read_b128 v[218:221], v217 offset:8704
	ds_read_b128 v[222:225], v217
	ds_read_b128 v[226:229], v217 offset:32
	ds_read_b128 v[232:235], v217 offset:8736
	ds_read_b128 v[236:239], v217 offset:64
	ds_read_b128 v[248:251], v217 offset:8768
	ds_read_b128 v[240:243], v217 offset:96
	ds_read_b128 v[174:177], v217 offset:8800
	v_bfi_b32 v80, v80, v231, v230
	v_bfi_b32 v78, v78, v231, v230
	v_bfi_b32 v77, v77, v231, v230
	v_bfi_b32 v76, v76, v231, v230
	v_bfi_b32 v75, v75, v231, v230
	v_bfi_b32 v74, v74, v231, v230
	v_bfi_b32 v73, v73, v231, v230
	v_bfi_b32 v72, v72, v231, v230
	v_bfi_b32 v71, v71, v231, v230
	v_bfi_b32 v70, v70, v231, v230
	v_bfi_b32 v69, v69, v231, v230
	v_bfi_b32 v68, v68, v231, v230
	v_bfi_b32 v67, v67, v231, v230
	v_bfi_b32 v96, v96, v231, v230
	v_bfi_b32 v95, v95, v231, v230
	v_bfi_b32 v94, v94, v231, v230
	v_bfi_b32 v93, v93, v231, v230
	v_bfi_b32 v92, v92, v231, v230
	v_bfi_b32 v91, v91, v231, v230
	v_bfi_b32 v90, v90, v231, v230
	v_bfi_b32 v89, v89, v231, v230
	v_bfi_b32 v88, v88, v231, v230
	v_bfi_b32 v87, v87, v231, v230
	v_bfi_b32 v86, v86, v231, v230
	v_bfi_b32 v85, v85, v231, v230
	v_bfi_b32 v84, v84, v231, v230
	s_setprio 1
	s_waitcnt lgkmcnt(6)
	v_mfma_f32_32x32x16_bf16 v[66:81], v[222:225], v[98:101], v[66:81]
	v_mfma_f32_32x32x16_bf16 v[82:97], v[218:221], v[98:101], v[82:97]
	s_waitcnt lgkmcnt(5)
	v_mfma_f32_32x32x16_bf16 v[66:81], v[226:229], v[102:105], v[66:81]
	s_waitcnt lgkmcnt(4)
	v_mfma_f32_32x32x16_bf16 v[82:97], v[232:235], v[102:105], v[82:97]
	s_waitcnt lgkmcnt(3)
	v_mfma_f32_32x32x16_bf16 v[66:81], v[236:239], v[106:109], v[66:81]
	s_waitcnt lgkmcnt(2)
	v_mfma_f32_32x32x16_bf16 v[82:97], v[248:251], v[106:109], v[82:97]
	s_waitcnt lgkmcnt(1)
	v_mfma_f32_32x32x16_bf16 v[66:81], v[240:243], v[110:113], v[66:81]
	s_waitcnt lgkmcnt(0)
	v_mfma_f32_32x32x16_bf16 v[82:97], v[174:177], v[110:113], v[82:97]
	s_setprio 0
	ds_read_b128 v[174:177], v217 offset:128
	ds_read_b128 v[218:221], v217 offset:160
	ds_read_b128 v[222:225], v217 offset:8832
	ds_read_b128 v[226:229], v217 offset:8864
	ds_read_b128 v[232:235], v217 offset:192
	ds_read_b128 v[236:239], v217 offset:224
	ds_read_b128 v[240:243], v217 offset:8896
	ds_read_b128 v[248:251], v217 offset:8928
	s_setprio 1
	s_waitcnt lgkmcnt(7)
	v_mfma_f32_32x32x16_bf16 v[66:81], v[174:177], v[114:117], v[66:81]
	s_waitcnt lgkmcnt(5)
	v_mfma_f32_32x32x16_bf16 v[82:97], v[222:225], v[114:117], v[82:97]
	v_mfma_f32_32x32x16_bf16 v[66:81], v[218:221], v[118:121], v[66:81]
	s_waitcnt lgkmcnt(4)
	v_mfma_f32_32x32x16_bf16 v[82:97], v[226:229], v[118:121], v[82:97]
	s_waitcnt lgkmcnt(3)
	v_mfma_f32_32x32x16_bf16 v[66:81], v[232:235], v[122:125], v[66:81]
	s_waitcnt lgkmcnt(1)
	v_mfma_f32_32x32x16_bf16 v[82:97], v[240:243], v[122:125], v[82:97]
	v_mfma_f32_32x32x16_bf16 v[66:81], v[236:239], v[126:129], v[66:81]
	s_waitcnt lgkmcnt(0)
	v_mfma_f32_32x32x16_bf16 v[82:97], v[248:251], v[126:129], v[82:97]
	s_setprio 0
	v_max3_f32 v174, v231, v66, v82
	s_nop 0
	v_max3_f32 v174, v174, v67, v83
	s_nop 0
	v_max3_f32 v174, v174, v68, v84
	s_nop 0
	v_max3_f32 v174, v174, v69, v85
	s_nop 0
	v_max3_f32 v174, v174, v70, v86
	s_nop 0
	v_max3_f32 v174, v174, v71, v87
	s_nop 0
	v_max3_f32 v174, v174, v72, v88
	s_nop 0
	v_max3_f32 v174, v174, v73, v89
	s_nop 0
	v_max3_f32 v174, v174, v74, v90
	s_nop 0
	v_max3_f32 v174, v174, v75, v91
	s_nop 0
	v_max3_f32 v174, v174, v76, v92
	s_nop 0
	v_max3_f32 v174, v174, v77, v93
	s_nop 0
	v_max3_f32 v174, v174, v78, v94
	s_nop 0
	v_max3_f32 v174, v174, v79, v95
	s_nop 0
	v_max3_f32 v174, v174, v80, v96
	s_nop 0
	v_max3_f32 v174, v174, v81, v97
	s_nop 0
	v_mov_b32_e32 v175, v174
	s_nop 1
	v_permlane32_swap_b32_e32 v174, v175
	v_max_f32_e32 v174, v174, v175
	v_cmp_gt_f32_e32 vcc, v174, v245
	s_cmp_eq_u64 vcc, 0
	s_cbranch_scc1 .Lsmf_0
	v_cndmask_b32_e32 v203, 0, v174, vcc
	v_mov_b32_e32 v175, 0x41000000
	v_cndmask_b32_e32 v245, v245, v175, vcc
	v_sub_f32_e32 v230, v230, v203
	v_max_f32_e32 v175, 0, v203
	v_exp_f32_e64 v202, -v175
	s_nop 0
	v_pk_mul_f32 v[64:65], v[64:65], v[202:203] op_sel_hi:[1,0]
	v_pk_mul_f32 v[62:63], v[62:63], v[202:203] op_sel_hi:[1,0]
	v_pk_mul_f32 v[60:61], v[60:61], v[202:203] op_sel_hi:[1,0]
	v_pk_mul_f32 v[58:59], v[58:59], v[202:203] op_sel_hi:[1,0]
	v_pk_mul_f32 v[56:57], v[56:57], v[202:203] op_sel_hi:[1,0]
	v_pk_mul_f32 v[54:55], v[54:55], v[202:203] op_sel_hi:[1,0]
	v_pk_mul_f32 v[52:53], v[52:53], v[202:203] op_sel_hi:[1,0]
	v_pk_mul_f32 v[50:51], v[50:51], v[202:203] op_sel_hi:[1,0]
	v_pk_mul_f32 v[48:49], v[48:49], v[202:203] op_sel_hi:[1,0]
	v_pk_mul_f32 v[46:47], v[46:47], v[202:203] op_sel_hi:[1,0]
	v_pk_mul_f32 v[44:45], v[44:45], v[202:203] op_sel_hi:[1,0]
	v_pk_mul_f32 v[42:43], v[42:43], v[202:203] op_sel_hi:[1,0]
	v_pk_mul_f32 v[40:41], v[40:41], v[202:203] op_sel_hi:[1,0]
	v_pk_mul_f32 v[38:39], v[38:39], v[202:203] op_sel_hi:[1,0]
	v_pk_mul_f32 v[36:37], v[36:37], v[202:203] op_sel_hi:[1,0]
	v_pk_mul_f32 v[34:35], v[34:35], v[202:203] op_sel_hi:[1,0]
	v_pk_mul_f32 v[32:33], v[32:33], v[202:203] op_sel_hi:[1,0]
	v_pk_mul_f32 v[30:31], v[30:31], v[202:203] op_sel_hi:[1,0]
	v_pk_mul_f32 v[28:29], v[28:29], v[202:203] op_sel_hi:[1,0]
	v_pk_mul_f32 v[26:27], v[26:27], v[202:203] op_sel_hi:[1,0]
	v_pk_mul_f32 v[24:25], v[24:25], v[202:203] op_sel_hi:[1,0]
	v_pk_mul_f32 v[22:23], v[22:23], v[202:203] op_sel_hi:[1,0]
	v_pk_mul_f32 v[20:21], v[20:21], v[202:203] op_sel_hi:[1,0]
	v_pk_mul_f32 v[18:19], v[18:19], v[202:203] op_sel_hi:[1,0]
	v_pk_mul_f32 v[16:17], v[16:17], v[202:203] op_sel_hi:[1,0]
	v_pk_mul_f32 v[14:15], v[14:15], v[202:203] op_sel_hi:[1,0]
	v_pk_mul_f32 v[12:13], v[12:13], v[202:203] op_sel_hi:[1,0]
	v_pk_mul_f32 v[10:11], v[10:11], v[202:203] op_sel_hi:[1,0]
	v_pk_mul_f32 v[8:9], v[8:9], v[202:203] op_sel_hi:[1,0]
	v_pk_mul_f32 v[6:7], v[6:7], v[202:203] op_sel_hi:[1,0]
	v_pk_mul_f32 v[4:5], v[4:5], v[202:203] op_sel_hi:[1,0]
	v_pk_mul_f32 v[2:3], v[2:3], v[202:203] op_sel_hi:[1,0]
.LBB0_70:
	v_pk_add_f32 v[66:67], v[66:67], v[202:203] op_sel:[0,1] op_sel_hi:[1,1] neg_lo:[0,1] neg_hi:[0,1]
	v_pk_add_f32 v[82:83], v[82:83], v[202:203] op_sel:[0,1] op_sel_hi:[1,1] neg_lo:[0,1] neg_hi:[0,1]
	v_exp_f32_e32 v66, v66
	v_exp_f32_e32 v67, v67
	v_exp_f32_e32 v82, v82
	v_exp_f32_e32 v83, v83
	v_pk_add_f32 v[68:69], v[68:69], v[202:203] op_sel:[0,1] op_sel_hi:[1,1] neg_lo:[0,1] neg_hi:[0,1]
	v_pk_add_f32 v[84:85], v[84:85], v[202:203] op_sel:[0,1] op_sel_hi:[1,1] neg_lo:[0,1] neg_hi:[0,1]
	v_exp_f32_e32 v68, v68
	v_exp_f32_e32 v69, v69
	v_exp_f32_e32 v84, v84
	v_exp_f32_e32 v85, v85
	v_pk_add_f32 v[174:175], v[66:67], v[82:83]
	v_pk_add_f32 v[70:71], v[70:71], v[202:203] op_sel:[0,1] op_sel_hi:[1,1] neg_lo:[0,1] neg_hi:[0,1]
	v_pk_add_f32 v[86:87], v[86:87], v[202:203] op_sel:[0,1] op_sel_hi:[1,1] neg_lo:[0,1] neg_hi:[0,1]
	v_exp_f32_e32 v70, v70
	v_exp_f32_e32 v71, v71
	v_exp_f32_e32 v86, v86
	v_exp_f32_e32 v87, v87
	v_pk_add_f32 v[174:175], v[174:175], v[68:69]
	v_pk_add_f32 v[174:175], v[174:175], v[84:85]
	v_pk_add_f32 v[72:73], v[72:73], v[202:203] op_sel:[0,1] op_sel_hi:[1,1] neg_lo:[0,1] neg_hi:[0,1]
	v_pk_add_f32 v[88:89], v[88:89], v[202:203] op_sel:[0,1] op_sel_hi:[1,1] neg_lo:[0,1] neg_hi:[0,1]
	v_exp_f32_e32 v72, v72
	v_exp_f32_e32 v73, v73
	v_exp_f32_e32 v88, v88
	v_exp_f32_e32 v89, v89
	v_pk_add_f32 v[174:175], v[174:175], v[70:71]
	v_pk_add_f32 v[174:175], v[174:175], v[86:87]
	v_pk_add_f32 v[74:75], v[74:75], v[202:203] op_sel:[0,1] op_sel_hi:[1,1] neg_lo:[0,1] neg_hi:[0,1]
	v_pk_add_f32 v[90:91], v[90:91], v[202:203] op_sel:[0,1] op_sel_hi:[1,1] neg_lo:[0,1] neg_hi:[0,1]
	v_exp_f32_e32 v74, v74
	v_exp_f32_e32 v75, v75
	v_exp_f32_e32 v90, v90
	v_exp_f32_e32 v91, v91
	v_pk_add_f32 v[174:175], v[174:175], v[72:73]
	v_pk_add_f32 v[174:175], v[174:175], v[88:89]
	v_pk_add_f32 v[76:77], v[76:77], v[202:203] op_sel:[0,1] op_sel_hi:[1,1] neg_lo:[0,1] neg_hi:[0,1]
	v_pk_add_f32 v[92:93], v[92:93], v[202:203] op_sel:[0,1] op_sel_hi:[1,1] neg_lo:[0,1] neg_hi:[0,1]
	v_exp_f32_e32 v76, v76
	v_exp_f32_e32 v77, v77
	v_exp_f32_e32 v92, v92
	v_exp_f32_e32 v93, v93
	v_pk_add_f32 v[174:175], v[174:175], v[74:75]
	v_pk_add_f32 v[174:175], v[174:175], v[90:91]
	v_pk_add_f32 v[78:79], v[78:79], v[202:203] op_sel:[0,1] op_sel_hi:[1,1] neg_lo:[0,1] neg_hi:[0,1]
	v_pk_add_f32 v[94:95], v[94:95], v[202:203] op_sel:[0,1] op_sel_hi:[1,1] neg_lo:[0,1] neg_hi:[0,1]
	v_exp_f32_e32 v78, v78
	v_exp_f32_e32 v79, v79
	v_exp_f32_e32 v94, v94
	v_exp_f32_e32 v95, v95
	v_pk_add_f32 v[174:175], v[174:175], v[76:77]
	v_pk_add_f32 v[174:175], v[174:175], v[92:93]
	v_pk_add_f32 v[80:81], v[80:81], v[202:203] op_sel:[0,1] op_sel_hi:[1,1] neg_lo:[0,1] neg_hi:[0,1]
	v_pk_add_f32 v[96:97], v[96:97], v[202:203] op_sel:[0,1] op_sel_hi:[1,1] neg_lo:[0,1] neg_hi:[0,1]
	v_exp_f32_e32 v80, v80
	v_exp_f32_e32 v81, v81
	v_exp_f32_e32 v96, v96
	v_exp_f32_e32 v97, v97
	v_pk_add_f32 v[174:175], v[174:175], v[78:79]
	v_pk_add_f32 v[174:175], v[174:175], v[94:95]
	s_nop 0
	v_pk_add_f32 v[174:175], v[174:175], v[80:81]
	v_pk_add_f32 v[174:175], v[174:175], v[96:97]
	v_add_f32_e32 v216, v174, v175
	s_branch .Lsmj_0
.Lsmf_0:
	v_mov_b32_e32 v202, 1.0
	v_exp_f32_e32 v66, v66
	v_exp_f32_e32 v67, v67
	v_exp_f32_e32 v82, v82
	v_exp_f32_e32 v83, v83
	v_exp_f32_e32 v68, v68
	v_exp_f32_e32 v69, v69
	v_exp_f32_e32 v84, v84
	v_exp_f32_e32 v85, v85
	v_pk_add_f32 v[174:175], v[66:67], v[82:83]
	v_exp_f32_e32 v70, v70
	v_exp_f32_e32 v71, v71
	v_exp_f32_e32 v86, v86
	v_exp_f32_e32 v87, v87
	v_pk_add_f32 v[174:175], v[174:175], v[68:69]
	v_pk_add_f32 v[174:175], v[174:175], v[84:85]
	v_exp_f32_e32 v72, v72
	v_exp_f32_e32 v73, v73
	v_exp_f32_e32 v88, v88
	v_exp_f32_e32 v89, v89
	v_pk_add_f32 v[174:175], v[174:175], v[70:71]
	v_pk_add_f32 v[174:175], v[174:175], v[86:87]
	v_exp_f32_e32 v74, v74
	v_exp_f32_e32 v75, v75
	v_exp_f32_e32 v90, v90
	v_exp_f32_e32 v91, v91
	v_pk_add_f32 v[174:175], v[174:175], v[72:73]
	v_pk_add_f32 v[174:175], v[174:175], v[88:89]
	v_exp_f32_e32 v76, v76
	v_exp_f32_e32 v77, v77
	v_exp_f32_e32 v92, v92
	v_exp_f32_e32 v93, v93
	v_pk_add_f32 v[174:175], v[174:175], v[74:75]
	v_pk_add_f32 v[174:175], v[174:175], v[90:91]
	v_exp_f32_e32 v78, v78
	v_exp_f32_e32 v79, v79
	v_exp_f32_e32 v94, v94
	v_exp_f32_e32 v95, v95
	v_pk_add_f32 v[174:175], v[174:175], v[76:77]
	v_pk_add_f32 v[174:175], v[174:175], v[92:93]
	v_exp_f32_e32 v80, v80
	v_exp_f32_e32 v81, v81
	v_exp_f32_e32 v96, v96
	v_exp_f32_e32 v97, v97
	v_pk_add_f32 v[174:175], v[174:175], v[78:79]
	v_pk_add_f32 v[174:175], v[174:175], v[94:95]
	s_nop 0
	v_pk_add_f32 v[174:175], v[174:175], v[80:81]
	v_pk_add_f32 v[174:175], v[174:175], v[96:97]
	v_add_f32_e32 v216, v174, v175
.Lsmj_0:
	v_fmac_f32_e32 v216, v193, v202
	v_add3_u32 v193, s47, v210, v211
	v_cvt_pk_bf16_f32 v174, v66, v67
	v_cvt_pk_bf16_f32 v175, v68, v69
	v_cvt_pk_bf16_f32 v176, v70, v71
	v_cvt_pk_bf16_f32 v177, v72, v73
	v_cvt_pk_bf16_f32 v218, v74, v75
	v_cvt_pk_bf16_f32 v219, v76, v77
	v_cvt_pk_bf16_f32 v220, v78, v79
	v_cvt_pk_bf16_f32 v221, v80, v81
	v_cvt_pk_bf16_f32 v222, v82, v83
	v_cvt_pk_bf16_f32 v223, v84, v85
	v_cvt_pk_bf16_f32 v224, v86, v87
	v_cvt_pk_bf16_f32 v225, v88, v89
	v_cvt_pk_bf16_f32 v226, v90, v91
	v_cvt_pk_bf16_f32 v227, v92, v93
	v_cvt_pk_bf16_f32 v228, v94, v95
	v_cvt_pk_bf16_f32 v229, v96, v97
	ds_read_b128 v[232:235], v193 offset:17408
	ds_read_b128 v[236:239], v193 offset:22016
	ds_read_b128 v[240:243], v193 offset:26624
	ds_read_b128 v[248:251], v193 offset:31232
	s_setprio 1
	s_waitcnt lgkmcnt(3)
	v_mfma_f32_32x32x16_bf16 v[50:65], v[232:235], v[174:177], v[50:65]
	s_waitcnt lgkmcnt(2)
	v_mfma_f32_32x32x16_bf16 v[34:49], v[236:239], v[174:177], v[34:49]
	s_waitcnt lgkmcnt(1)
	v_mfma_f32_32x32x16_bf16 v[18:33], v[240:243], v[174:177], v[18:33]
	s_waitcnt lgkmcnt(0)
	v_mfma_f32_32x32x16_bf16 v[2:17], v[248:251], v[174:177], v[2:17]
	s_setprio 0
	ds_read_b128 v[174:177], v193 offset:17440
	ds_read_b128 v[232:235], v193 offset:22048
	ds_read_b128 v[236:239], v193 offset:26656
	ds_read_b128 v[240:243], v193 offset:31264
	s_setprio 1
	s_waitcnt lgkmcnt(3)
	v_mfma_f32_32x32x16_bf16 v[50:65], v[174:177], v[218:221], v[50:65]
	s_waitcnt lgkmcnt(2)
	v_mfma_f32_32x32x16_bf16 v[34:49], v[232:235], v[218:221], v[34:49]
	s_waitcnt lgkmcnt(1)
	v_mfma_f32_32x32x16_bf16 v[18:33], v[236:239], v[218:221], v[18:33]
	s_waitcnt lgkmcnt(0)
	v_mfma_f32_32x32x16_bf16 v[2:17], v[240:243], v[218:221], v[2:17]
	s_setprio 0
	ds_read_b128 v[174:177], v193 offset:17472
	ds_read_b128 v[218:221], v193 offset:22080
	ds_read_b128 v[232:235], v193 offset:26688
	ds_read_b128 v[236:239], v193 offset:31296
	s_setprio 1
	s_waitcnt lgkmcnt(3)
	v_mfma_f32_32x32x16_bf16 v[50:65], v[174:177], v[222:225], v[50:65]
	s_waitcnt lgkmcnt(2)
	v_mfma_f32_32x32x16_bf16 v[34:49], v[218:221], v[222:225], v[34:49]
	s_waitcnt lgkmcnt(1)
	v_mfma_f32_32x32x16_bf16 v[18:33], v[232:235], v[222:225], v[18:33]
	s_waitcnt lgkmcnt(0)
	v_mfma_f32_32x32x16_bf16 v[2:17], v[236:239], v[222:225], v[2:17]
	s_setprio 0
	ds_read_b128 v[174:177], v193 offset:17504
	ds_read_b128 v[218:221], v193 offset:22112
	ds_read_b128 v[222:225], v193 offset:26720
	ds_read_b128 v[232:235], v193 offset:31328
	s_setprio 1
	s_waitcnt lgkmcnt(3)
	v_mfma_f32_32x32x16_bf16 v[50:65], v[174:177], v[226:229], v[50:65]
	s_waitcnt lgkmcnt(2)
	v_mfma_f32_32x32x16_bf16 v[34:49], v[218:221], v[226:229], v[34:49]
	s_waitcnt lgkmcnt(1)
	v_mfma_f32_32x32x16_bf16 v[18:33], v[222:225], v[226:229], v[18:33]
	s_waitcnt lgkmcnt(0)
	v_mfma_f32_32x32x16_bf16 v[2:17], v[232:235], v[226:229], v[2:17]
	s_setprio 0
.LBB0_71:
	s_andn2_saveexec_b64 s[0:1], s[0:1]
	s_cbranch_execz .LBB0_78
	s_cmp_eq_u32 s44, 3
	s_cbranch_scc1 .LBB0_76
	v_max3_f32 v174, v231, v66, v82
	s_nop 0
	v_max3_f32 v174, v174, v67, v83
	s_nop 0
	v_max3_f32 v174, v174, v68, v84
	s_nop 0
	v_max3_f32 v174, v174, v69, v85
	s_nop 0
	v_max3_f32 v174, v174, v70, v86
	s_nop 0
	v_max3_f32 v174, v174, v71, v87
	s_nop 0
	v_max3_f32 v174, v174, v72, v88
	s_nop 0
	v_max3_f32 v174, v174, v73, v89
	s_nop 0
	v_max3_f32 v174, v174, v74, v90
	s_nop 0
	v_max3_f32 v174, v174, v75, v91
	s_nop 0
	v_max3_f32 v174, v174, v76, v92
	s_nop 0
	v_max3_f32 v174, v174, v77, v93
	s_nop 0
	v_max3_f32 v174, v174, v78, v94
	s_nop 0
	v_max3_f32 v174, v174, v79, v95
	s_nop 0
	v_max3_f32 v174, v174, v80, v96
	s_nop 0
	v_max3_f32 v174, v174, v81, v97
	s_nop 0
	v_mov_b32_e32 v175, v174
	s_nop 1
	v_permlane32_swap_b32_e32 v174, v175
	v_max_f32_e32 v174, v174, v175
	v_cmp_gt_f32_e32 vcc, v174, v245
	s_cmp_eq_u64 vcc, 0
	s_cbranch_scc1 .Lsmf_1
	v_cndmask_b32_e32 v216, 0, v174, vcc
	v_mov_b32_e32 v175, 0x41000000
	v_cndmask_b32_e32 v245, v245, v175, vcc
	v_sub_f32_e32 v230, v230, v216
	v_max_f32_e32 v175, 0, v216
	v_exp_f32_e64 v202, -v175
	s_nop 0
	v_pk_mul_f32 v[64:65], v[64:65], v[202:203] op_sel_hi:[1,0]
	v_pk_mul_f32 v[62:63], v[62:63], v[202:203] op_sel_hi:[1,0]
	v_pk_mul_f32 v[60:61], v[60:61], v[202:203] op_sel_hi:[1,0]
	v_pk_mul_f32 v[58:59], v[58:59], v[202:203] op_sel_hi:[1,0]
	v_pk_mul_f32 v[56:57], v[56:57], v[202:203] op_sel_hi:[1,0]
	v_pk_mul_f32 v[54:55], v[54:55], v[202:203] op_sel_hi:[1,0]
	v_pk_mul_f32 v[52:53], v[52:53], v[202:203] op_sel_hi:[1,0]
	v_pk_mul_f32 v[50:51], v[50:51], v[202:203] op_sel_hi:[1,0]
	v_pk_mul_f32 v[48:49], v[48:49], v[202:203] op_sel_hi:[1,0]
	v_pk_mul_f32 v[46:47], v[46:47], v[202:203] op_sel_hi:[1,0]
	v_pk_mul_f32 v[44:45], v[44:45], v[202:203] op_sel_hi:[1,0]
	v_pk_mul_f32 v[42:43], v[42:43], v[202:203] op_sel_hi:[1,0]
	v_pk_mul_f32 v[40:41], v[40:41], v[202:203] op_sel_hi:[1,0]
	v_pk_mul_f32 v[38:39], v[38:39], v[202:203] op_sel_hi:[1,0]
	v_pk_mul_f32 v[36:37], v[36:37], v[202:203] op_sel_hi:[1,0]
	v_pk_mul_f32 v[34:35], v[34:35], v[202:203] op_sel_hi:[1,0]
	v_pk_mul_f32 v[32:33], v[32:33], v[202:203] op_sel_hi:[1,0]
	v_pk_mul_f32 v[30:31], v[30:31], v[202:203] op_sel_hi:[1,0]
	v_pk_mul_f32 v[28:29], v[28:29], v[202:203] op_sel_hi:[1,0]
	v_pk_mul_f32 v[26:27], v[26:27], v[202:203] op_sel_hi:[1,0]
	v_pk_mul_f32 v[24:25], v[24:25], v[202:203] op_sel_hi:[1,0]
	v_pk_mul_f32 v[22:23], v[22:23], v[202:203] op_sel_hi:[1,0]
	v_pk_mul_f32 v[20:21], v[20:21], v[202:203] op_sel_hi:[1,0]
	v_pk_mul_f32 v[18:19], v[18:19], v[202:203] op_sel_hi:[1,0]
	v_pk_mul_f32 v[16:17], v[16:17], v[202:203] op_sel_hi:[1,0]
	v_pk_mul_f32 v[14:15], v[14:15], v[202:203] op_sel_hi:[1,0]
	v_pk_mul_f32 v[12:13], v[12:13], v[202:203] op_sel_hi:[1,0]
	v_pk_mul_f32 v[10:11], v[10:11], v[202:203] op_sel_hi:[1,0]
	v_pk_mul_f32 v[8:9], v[8:9], v[202:203] op_sel_hi:[1,0]
	v_pk_mul_f32 v[6:7], v[6:7], v[202:203] op_sel_hi:[1,0]
	v_pk_mul_f32 v[4:5], v[4:5], v[202:203] op_sel_hi:[1,0]
	v_pk_mul_f32 v[2:3], v[2:3], v[202:203] op_sel_hi:[1,0]
.LBB0_75:
	v_pk_add_f32 v[66:67], v[66:67], v[216:217] op_sel_hi:[1,0] neg_lo:[0,1] neg_hi:[0,1]
	v_pk_add_f32 v[82:83], v[82:83], v[216:217] op_sel_hi:[1,0] neg_lo:[0,1] neg_hi:[0,1]
	v_exp_f32_e32 v66, v66
	v_exp_f32_e32 v67, v67
	v_exp_f32_e32 v82, v82
	v_exp_f32_e32 v83, v83
	v_pk_add_f32 v[68:69], v[68:69], v[216:217] op_sel_hi:[1,0] neg_lo:[0,1] neg_hi:[0,1]
	v_pk_add_f32 v[84:85], v[84:85], v[216:217] op_sel_hi:[1,0] neg_lo:[0,1] neg_hi:[0,1]
	v_exp_f32_e32 v68, v68
	v_exp_f32_e32 v69, v69
	v_exp_f32_e32 v84, v84
	v_exp_f32_e32 v85, v85
	v_pk_add_f32 v[174:175], v[66:67], v[82:83]
	v_pk_add_f32 v[70:71], v[70:71], v[216:217] op_sel_hi:[1,0] neg_lo:[0,1] neg_hi:[0,1]
	v_pk_add_f32 v[86:87], v[86:87], v[216:217] op_sel_hi:[1,0] neg_lo:[0,1] neg_hi:[0,1]
	v_exp_f32_e32 v70, v70
	v_exp_f32_e32 v71, v71
	v_exp_f32_e32 v86, v86
	v_exp_f32_e32 v87, v87
	v_pk_add_f32 v[174:175], v[174:175], v[68:69]
	v_pk_add_f32 v[174:175], v[174:175], v[84:85]
	v_pk_add_f32 v[72:73], v[72:73], v[216:217] op_sel_hi:[1,0] neg_lo:[0,1] neg_hi:[0,1]
	v_pk_add_f32 v[88:89], v[88:89], v[216:217] op_sel_hi:[1,0] neg_lo:[0,1] neg_hi:[0,1]
	v_exp_f32_e32 v72, v72
	v_exp_f32_e32 v73, v73
	v_exp_f32_e32 v88, v88
	v_exp_f32_e32 v89, v89
	v_pk_add_f32 v[174:175], v[174:175], v[70:71]
	v_pk_add_f32 v[174:175], v[174:175], v[86:87]
	v_pk_add_f32 v[74:75], v[74:75], v[216:217] op_sel_hi:[1,0] neg_lo:[0,1] neg_hi:[0,1]
	v_pk_add_f32 v[90:91], v[90:91], v[216:217] op_sel_hi:[1,0] neg_lo:[0,1] neg_hi:[0,1]
	v_exp_f32_e32 v74, v74
	v_exp_f32_e32 v75, v75
	v_exp_f32_e32 v90, v90
	v_exp_f32_e32 v91, v91
	v_pk_add_f32 v[174:175], v[174:175], v[72:73]
	v_pk_add_f32 v[174:175], v[174:175], v[88:89]
	v_pk_add_f32 v[76:77], v[76:77], v[216:217] op_sel_hi:[1,0] neg_lo:[0,1] neg_hi:[0,1]
	v_pk_add_f32 v[92:93], v[92:93], v[216:217] op_sel_hi:[1,0] neg_lo:[0,1] neg_hi:[0,1]
	v_exp_f32_e32 v76, v76
	v_exp_f32_e32 v77, v77
	v_exp_f32_e32 v92, v92
	v_exp_f32_e32 v93, v93
	v_pk_add_f32 v[174:175], v[174:175], v[74:75]
	v_pk_add_f32 v[174:175], v[174:175], v[90:91]
	v_pk_add_f32 v[78:79], v[78:79], v[216:217] op_sel_hi:[1,0] neg_lo:[0,1] neg_hi:[0,1]
	v_pk_add_f32 v[94:95], v[94:95], v[216:217] op_sel_hi:[1,0] neg_lo:[0,1] neg_hi:[0,1]
	v_exp_f32_e32 v78, v78
	v_exp_f32_e32 v79, v79
	v_exp_f32_e32 v94, v94
	v_exp_f32_e32 v95, v95
	v_pk_add_f32 v[174:175], v[174:175], v[76:77]
	v_pk_add_f32 v[174:175], v[174:175], v[92:93]
	v_pk_add_f32 v[80:81], v[80:81], v[216:217] op_sel_hi:[1,0] neg_lo:[0,1] neg_hi:[0,1]
	v_pk_add_f32 v[96:97], v[96:97], v[216:217] op_sel_hi:[1,0] neg_lo:[0,1] neg_hi:[0,1]
	v_exp_f32_e32 v80, v80
	v_exp_f32_e32 v81, v81
	v_exp_f32_e32 v96, v96
	v_exp_f32_e32 v97, v97
	v_pk_add_f32 v[174:175], v[174:175], v[78:79]
	v_pk_add_f32 v[174:175], v[174:175], v[94:95]
	s_mul_i32 s48, s48, 0x8c00
	s_nop 0
	v_pk_add_f32 v[174:175], v[174:175], v[80:81]
	v_pk_add_f32 v[174:175], v[174:175], v[96:97]
	v_add_f32_e32 v216, v174, v175
	s_branch .Lsmj_1
.Lsmf_1:
	v_mov_b32_e32 v202, 1.0
	v_exp_f32_e32 v66, v66
	v_exp_f32_e32 v67, v67
	v_exp_f32_e32 v82, v82
	v_exp_f32_e32 v83, v83
	v_exp_f32_e32 v68, v68
	v_exp_f32_e32 v69, v69
	v_exp_f32_e32 v84, v84
	v_exp_f32_e32 v85, v85
	v_pk_add_f32 v[174:175], v[66:67], v[82:83]
	v_exp_f32_e32 v70, v70
	v_exp_f32_e32 v71, v71
	v_exp_f32_e32 v86, v86
	v_exp_f32_e32 v87, v87
	v_pk_add_f32 v[174:175], v[174:175], v[68:69]
	v_pk_add_f32 v[174:175], v[174:175], v[84:85]
	v_exp_f32_e32 v72, v72
	v_exp_f32_e32 v73, v73
	v_exp_f32_e32 v88, v88
	v_exp_f32_e32 v89, v89
	v_pk_add_f32 v[174:175], v[174:175], v[70:71]
	v_pk_add_f32 v[174:175], v[174:175], v[86:87]
	v_exp_f32_e32 v74, v74
	v_exp_f32_e32 v75, v75
	v_exp_f32_e32 v90, v90
	v_exp_f32_e32 v91, v91
	v_pk_add_f32 v[174:175], v[174:175], v[72:73]
	v_pk_add_f32 v[174:175], v[174:175], v[88:89]
	v_exp_f32_e32 v76, v76
	v_exp_f32_e32 v77, v77
	v_exp_f32_e32 v92, v92
	v_exp_f32_e32 v93, v93
	v_pk_add_f32 v[174:175], v[174:175], v[74:75]
	v_pk_add_f32 v[174:175], v[174:175], v[90:91]
	v_exp_f32_e32 v78, v78
	v_exp_f32_e32 v79, v79
	v_exp_f32_e32 v94, v94
	v_exp_f32_e32 v95, v95
	v_pk_add_f32 v[174:175], v[174:175], v[76:77]
	v_pk_add_f32 v[174:175], v[174:175], v[92:93]
	v_exp_f32_e32 v80, v80
	v_exp_f32_e32 v81, v81
	v_exp_f32_e32 v96, v96
	v_exp_f32_e32 v97, v97
	v_pk_add_f32 v[174:175], v[174:175], v[78:79]
	v_pk_add_f32 v[174:175], v[174:175], v[94:95]
	s_mul_i32 s48, s48, 0x8c00
	s_nop 0
	v_pk_add_f32 v[174:175], v[174:175], v[80:81]
	v_pk_add_f32 v[174:175], v[174:175], v[96:97]
	v_add_f32_e32 v216, v174, v175
.Lsmj_1:
	v_add_u32_e32 v174, s48, v212
	v_cvt_pk_bf16_f32 v66, v66, v67
	v_cvt_pk_bf16_f32 v67, v68, v69
	v_cvt_pk_bf16_f32 v68, v70, v71
	v_cvt_pk_bf16_f32 v69, v72, v73
	v_cvt_pk_bf16_f32 v70, v74, v75
	v_cvt_pk_bf16_f32 v71, v76, v77
	v_cvt_pk_bf16_f32 v72, v78, v79
	v_cvt_pk_bf16_f32 v73, v80, v81
	v_cvt_pk_bf16_f32 v74, v82, v83
	v_cvt_pk_bf16_f32 v75, v84, v85
	v_cvt_pk_bf16_f32 v76, v86, v87
	v_cvt_pk_bf16_f32 v77, v88, v89
	v_cvt_pk_bf16_f32 v78, v90, v91
	v_cvt_pk_bf16_f32 v79, v92, v93
	v_cvt_pk_bf16_f32 v80, v94, v95
	v_cvt_pk_bf16_f32 v81, v96, v97
	ds_read_b128 v[82:85], v174 offset:17408
	ds_read_b128 v[86:89], v174 offset:22016
	ds_read_b128 v[90:93], v174 offset:26624
	ds_read_b128 v[94:97], v174 offset:31232
	v_fmac_f32_e32 v216, v193, v202
	s_setprio 1
	s_waitcnt lgkmcnt(3)
	v_mfma_f32_32x32x16_bf16 v[50:65], v[82:85], v[66:69], v[50:65]
	s_waitcnt lgkmcnt(2)
	v_mfma_f32_32x32x16_bf16 v[34:49], v[86:89], v[66:69], v[34:49]
	s_waitcnt lgkmcnt(1)
	v_mfma_f32_32x32x16_bf16 v[18:33], v[90:93], v[66:69], v[18:33]
	s_waitcnt lgkmcnt(0)
	v_mfma_f32_32x32x16_bf16 v[2:17], v[94:97], v[66:69], v[2:17]
	s_setprio 0
	ds_read_b128 v[66:69], v174 offset:17440
	ds_read_b128 v[82:85], v174 offset:22048
	ds_read_b128 v[86:89], v174 offset:26656
	ds_read_b128 v[90:93], v174 offset:31264
	s_setprio 1
	s_waitcnt lgkmcnt(3)
	v_mfma_f32_32x32x16_bf16 v[50:65], v[66:69], v[70:73], v[50:65]
	s_waitcnt lgkmcnt(2)
	v_mfma_f32_32x32x16_bf16 v[34:49], v[82:85], v[70:73], v[34:49]
	s_waitcnt lgkmcnt(1)
	v_mfma_f32_32x32x16_bf16 v[18:33], v[86:89], v[70:73], v[18:33]
	s_waitcnt lgkmcnt(0)
	v_mfma_f32_32x32x16_bf16 v[2:17], v[90:93], v[70:73], v[2:17]
	s_setprio 0
	ds_read_b128 v[66:69], v174 offset:17472
	ds_read_b128 v[70:73], v174 offset:22080
	ds_read_b128 v[82:85], v174 offset:26688
	ds_read_b128 v[86:89], v174 offset:31296
	s_setprio 1
	s_waitcnt lgkmcnt(3)
	v_mfma_f32_32x32x16_bf16 v[50:65], v[66:69], v[74:77], v[50:65]
	s_waitcnt lgkmcnt(2)
	v_mfma_f32_32x32x16_bf16 v[34:49], v[70:73], v[74:77], v[34:49]
	s_waitcnt lgkmcnt(1)
	v_mfma_f32_32x32x16_bf16 v[18:33], v[82:85], v[74:77], v[18:33]
	s_waitcnt lgkmcnt(0)
	v_mfma_f32_32x32x16_bf16 v[2:17], v[86:89], v[74:77], v[2:17]
	s_setprio 0
	ds_read_b128 v[66:69], v174 offset:17504
	ds_read_b128 v[70:73], v174 offset:22112
	ds_read_b128 v[74:77], v174 offset:26720
	ds_read_b128 v[82:85], v174 offset:31328
	s_setprio 1
	s_waitcnt lgkmcnt(3)
	v_mfma_f32_32x32x16_bf16 v[50:65], v[66:69], v[78:81], v[50:65]
	s_waitcnt lgkmcnt(2)
	v_mfma_f32_32x32x16_bf16 v[34:49], v[70:73], v[78:81], v[34:49]
	s_waitcnt lgkmcnt(1)
	v_mfma_f32_32x32x16_bf16 v[18:33], v[74:77], v[78:81], v[18:33]
	s_waitcnt lgkmcnt(0)
	v_mfma_f32_32x32x16_bf16 v[2:17], v[82:85], v[78:81], v[2:17]
	s_setprio 0
	s_branch .LBB0_77

.LBB0_77:
	v_not_b32_e32 v66, v218
	v_not_b32_e32 v82, v203
	v_bfe_i32 v83, v66, 0, 1
	v_bfe_i32 v174, v82, 0, 1
	v_bfe_i32 v67, v66, 1, 1
	v_bfe_i32 v175, v82, 1, 1
	v_bfe_i32 v68, v66, 2, 1
	v_bfe_i32 v84, v82, 2, 1
	v_bfe_i32 v69, v66, 3, 1
	v_bfe_i32 v85, v82, 3, 1
	v_bfe_i32 v70, v66, 8, 1
	v_bfe_i32 v86, v82, 8, 1
	v_bfe_i32 v71, v66, 9, 1
	v_bfe_i32 v87, v82, 9, 1
	v_bfe_i32 v72, v66, 10, 1
	v_bfe_i32 v88, v82, 10, 1
	v_bfe_i32 v73, v66, 11, 1
	v_bfe_i32 v89, v82, 11, 1
	v_bfe_i32 v74, v66, 16, 1
	v_bfe_i32 v90, v82, 16, 1
	v_bfe_i32 v75, v66, 17, 1
	v_bfe_i32 v91, v82, 17, 1
	v_bfe_i32 v76, v66, 18, 1
	v_bfe_i32 v92, v82, 18, 1
	v_bfe_i32 v77, v66, 19, 1
	v_bfe_i32 v93, v82, 19, 1
	v_bfe_i32 v78, v66, 24, 1
	v_bfe_i32 v94, v82, 24, 1
	v_bfe_i32 v79, v66, 25, 1
	v_bfe_i32 v95, v82, 25, 1
	v_bfe_i32 v80, v66, 26, 1
	v_bfe_i32 v96, v82, 26, 1
	v_bfe_i32 v66, v66, 27, 1
	v_bfe_i32 v82, v82, 27, 1
	s_nop 0
	v_bfi_b32 v79, v79, v231, v230
	v_bfi_b32 v81, v66, v231, v230
	v_bfi_b32 v66, v83, v231, v230
	v_bfi_b32 v97, v82, v231, v230
	v_bfi_b32 v83, v175, v231, v230
	v_bfi_b32 v82, v174, v231, v230
	ds_read_b128 v[174:177], v217 offset:8704
	ds_read_b128 v[218:221], v217
	ds_read_b128 v[222:225], v217 offset:32
	ds_read_b128 v[226:229], v217 offset:8736
	ds_read_b128 v[232:235], v217 offset:64
	ds_read_b128 v[236:239], v217 offset:8768
	ds_read_b128 v[240:243], v217 offset:96
	ds_read_b128 v[248:251], v217 offset:8800
	v_bfi_b32 v80, v80, v231, v230
	v_bfi_b32 v78, v78, v231, v230
	v_bfi_b32 v77, v77, v231, v230
	v_bfi_b32 v76, v76, v231, v230
	v_bfi_b32 v75, v75, v231, v230
	v_bfi_b32 v74, v74, v231, v230
	v_bfi_b32 v73, v73, v231, v230
	v_bfi_b32 v72, v72, v231, v230
	v_bfi_b32 v71, v71, v231, v230
	v_bfi_b32 v70, v70, v231, v230
	v_bfi_b32 v69, v69, v231, v230
	v_bfi_b32 v68, v68, v231, v230
	v_bfi_b32 v67, v67, v231, v230
	v_bfi_b32 v96, v96, v231, v230
	v_bfi_b32 v95, v95, v231, v230
	v_bfi_b32 v94, v94, v231, v230
	v_bfi_b32 v93, v93, v231, v230
	v_bfi_b32 v92, v92, v231, v230
	v_bfi_b32 v91, v91, v231, v230
	v_bfi_b32 v90, v90, v231, v230
	v_bfi_b32 v89, v89, v231, v230
	v_bfi_b32 v88, v88, v231, v230
	v_bfi_b32 v87, v87, v231, v230
	v_bfi_b32 v86, v86, v231, v230
	v_bfi_b32 v85, v85, v231, v230
	v_bfi_b32 v84, v84, v231, v230
	s_setprio 1
	s_waitcnt lgkmcnt(6)
	v_mfma_f32_32x32x16_bf16 v[66:81], v[218:221], v[98:101], v[66:81]
	v_mfma_f32_32x32x16_bf16 v[82:97], v[174:177], v[98:101], v[82:97]
	s_waitcnt lgkmcnt(5)
	v_mfma_f32_32x32x16_bf16 v[66:81], v[222:225], v[102:105], v[66:81]
	s_waitcnt lgkmcnt(4)
	v_mfma_f32_32x32x16_bf16 v[82:97], v[226:229], v[102:105], v[82:97]
	s_waitcnt lgkmcnt(3)
	v_mfma_f32_32x32x16_bf16 v[66:81], v[232:235], v[106:109], v[66:81]
	s_waitcnt lgkmcnt(2)
	v_mfma_f32_32x32x16_bf16 v[82:97], v[236:239], v[106:109], v[82:97]
	s_waitcnt lgkmcnt(1)
	v_mfma_f32_32x32x16_bf16 v[66:81], v[240:243], v[110:113], v[66:81]
	s_waitcnt lgkmcnt(0)
	v_mfma_f32_32x32x16_bf16 v[82:97], v[248:251], v[110:113], v[82:97]
	s_setprio 0
	ds_read_b128 v[174:177], v217 offset:128
	ds_read_b128 v[218:221], v217 offset:160
	ds_read_b128 v[222:225], v217 offset:8832
	ds_read_b128 v[226:229], v217 offset:8864
	ds_read_b128 v[232:235], v217 offset:192
	ds_read_b128 v[236:239], v217 offset:224
	ds_read_b128 v[240:243], v217 offset:8896
	ds_read_b128 v[248:251], v217 offset:8928
	s_setprio 1
	s_waitcnt lgkmcnt(7)
	v_mfma_f32_32x32x16_bf16 v[66:81], v[174:177], v[114:117], v[66:81]
	s_waitcnt lgkmcnt(5)
	v_mfma_f32_32x32x16_bf16 v[82:97], v[222:225], v[114:117], v[82:97]
	v_mfma_f32_32x32x16_bf16 v[66:81], v[218:221], v[118:121], v[66:81]
	s_waitcnt lgkmcnt(4)
	v_mfma_f32_32x32x16_bf16 v[82:97], v[226:229], v[118:121], v[82:97]
	s_waitcnt lgkmcnt(3)
	v_mfma_f32_32x32x16_bf16 v[66:81], v[232:235], v[122:125], v[66:81]
	s_waitcnt lgkmcnt(1)
	v_mfma_f32_32x32x16_bf16 v[82:97], v[240:243], v[122:125], v[82:97]
	v_mfma_f32_32x32x16_bf16 v[66:81], v[236:239], v[126:129], v[66:81]
	s_waitcnt lgkmcnt(0)
	v_mfma_f32_32x32x16_bf16 v[82:97], v[248:251], v[126:129], v[82:97]
	s_setprio 0

.LBB0_90:
	v_not_b32_e32 v66, v218
	v_not_b32_e32 v82, v205
	v_bfe_i32 v83, v66, 0, 1
	v_bfe_i32 v174, v82, 0, 1
	v_bfe_i32 v67, v66, 1, 1
	v_bfe_i32 v175, v82, 1, 1
	v_bfe_i32 v68, v66, 2, 1
	v_bfe_i32 v84, v82, 2, 1
	v_bfe_i32 v69, v66, 3, 1
	v_bfe_i32 v85, v82, 3, 1
	v_bfe_i32 v70, v66, 8, 1
	v_bfe_i32 v86, v82, 8, 1
	v_bfe_i32 v71, v66, 9, 1
	v_bfe_i32 v87, v82, 9, 1
	v_bfe_i32 v72, v66, 10, 1
	v_bfe_i32 v88, v82, 10, 1
	v_bfe_i32 v73, v66, 11, 1
	v_bfe_i32 v89, v82, 11, 1
	v_bfe_i32 v74, v66, 16, 1
	v_bfe_i32 v90, v82, 16, 1
	v_bfe_i32 v75, v66, 17, 1
	v_bfe_i32 v91, v82, 17, 1
	v_bfe_i32 v76, v66, 18, 1
	v_bfe_i32 v92, v82, 18, 1
	v_bfe_i32 v77, v66, 19, 1
	v_bfe_i32 v93, v82, 19, 1
	v_bfe_i32 v78, v66, 24, 1
	v_bfe_i32 v94, v82, 24, 1
	v_bfe_i32 v79, v66, 25, 1
	v_bfe_i32 v95, v82, 25, 1
	v_bfe_i32 v80, v66, 26, 1
	v_bfe_i32 v96, v82, 26, 1
	v_bfe_i32 v66, v66, 27, 1
	v_bfe_i32 v82, v82, 27, 1
	s_nop 0
	v_bfi_b32 v79, v79, v231, v230
	v_bfi_b32 v81, v66, v231, v230
	v_bfi_b32 v66, v83, v231, v230
	v_bfi_b32 v97, v82, v231, v230
	v_bfi_b32 v83, v175, v231, v230
	v_bfi_b32 v82, v174, v231, v230
	ds_read_b128 v[174:177], v217 offset:8704
	ds_read_b128 v[218:221], v217
	ds_read_b128 v[222:225], v217 offset:32
	ds_read_b128 v[226:229], v217 offset:8736
	ds_read_b128 v[232:235], v217 offset:64
	ds_read_b128 v[236:239], v217 offset:8768
	ds_read_b128 v[240:243], v217 offset:96
	ds_read_b128 v[248:251], v217 offset:8800
	v_bfi_b32 v80, v80, v231, v230
	v_bfi_b32 v78, v78, v231, v230
	v_bfi_b32 v77, v77, v231, v230
	v_bfi_b32 v76, v76, v231, v230
	v_bfi_b32 v75, v75, v231, v230
	v_bfi_b32 v74, v74, v231, v230
	v_bfi_b32 v73, v73, v231, v230
	v_bfi_b32 v72, v72, v231, v230
	v_bfi_b32 v71, v71, v231, v230
	v_bfi_b32 v70, v70, v231, v230
	v_bfi_b32 v69, v69, v231, v230
	v_bfi_b32 v68, v68, v231, v230
	v_bfi_b32 v67, v67, v231, v230
	v_bfi_b32 v96, v96, v231, v230
	v_bfi_b32 v95, v95, v231, v230
	v_bfi_b32 v94, v94, v231, v230
	v_bfi_b32 v93, v93, v231, v230
	v_bfi_b32 v92, v92, v231, v230
	v_bfi_b32 v91, v91, v231, v230
	v_bfi_b32 v90, v90, v231, v230
	v_bfi_b32 v89, v89, v231, v230
	v_bfi_b32 v88, v88, v231, v230
	v_bfi_b32 v87, v87, v231, v230
	v_bfi_b32 v86, v86, v231, v230
	v_bfi_b32 v85, v85, v231, v230
	v_bfi_b32 v84, v84, v231, v230
	s_setprio 1
	s_waitcnt lgkmcnt(6)
	v_mfma_f32_32x32x16_bf16 v[66:81], v[218:221], v[98:101], v[66:81]
	v_mfma_f32_32x32x16_bf16 v[82:97], v[174:177], v[98:101], v[82:97]
	s_waitcnt lgkmcnt(5)
	v_mfma_f32_32x32x16_bf16 v[66:81], v[222:225], v[102:105], v[66:81]
	s_waitcnt lgkmcnt(4)
	v_mfma_f32_32x32x16_bf16 v[82:97], v[226:229], v[102:105], v[82:97]
	s_waitcnt lgkmcnt(3)
	v_mfma_f32_32x32x16_bf16 v[66:81], v[232:235], v[106:109], v[66:81]
	s_waitcnt lgkmcnt(2)
	v_mfma_f32_32x32x16_bf16 v[82:97], v[236:239], v[106:109], v[82:97]
	s_waitcnt lgkmcnt(1)
	v_mfma_f32_32x32x16_bf16 v[66:81], v[240:243], v[110:113], v[66:81]
	s_waitcnt lgkmcnt(0)
	v_mfma_f32_32x32x16_bf16 v[82:97], v[248:251], v[110:113], v[82:97]
	s_setprio 0
	ds_read_b128 v[174:177], v217 offset:128
	ds_read_b128 v[218:221], v217 offset:160
	ds_read_b128 v[222:225], v217 offset:8832
	ds_read_b128 v[226:229], v217 offset:8864
	ds_read_b128 v[232:235], v217 offset:192
	ds_read_b128 v[236:239], v217 offset:224
	ds_read_b128 v[240:243], v217 offset:8896
	ds_read_b128 v[248:251], v217 offset:8928
	s_setprio 1
	s_waitcnt lgkmcnt(7)
	v_mfma_f32_32x32x16_bf16 v[66:81], v[174:177], v[114:117], v[66:81]
	s_waitcnt lgkmcnt(5)
	v_mfma_f32_32x32x16_bf16 v[82:97], v[222:225], v[114:117], v[82:97]
	v_mfma_f32_32x32x16_bf16 v[66:81], v[218:221], v[118:121], v[66:81]
	s_waitcnt lgkmcnt(4)
	v_mfma_f32_32x32x16_bf16 v[82:97], v[226:229], v[118:121], v[82:97]
	s_waitcnt lgkmcnt(3)
	v_mfma_f32_32x32x16_bf16 v[66:81], v[232:235], v[122:125], v[66:81]
	s_waitcnt lgkmcnt(1)
	v_mfma_f32_32x32x16_bf16 v[82:97], v[240:243], v[122:125], v[82:97]
	v_mfma_f32_32x32x16_bf16 v[66:81], v[236:239], v[126:129], v[66:81]
	s_waitcnt lgkmcnt(0)
	v_mfma_f32_32x32x16_bf16 v[82:97], v[248:251], v[126:129], v[82:97]
	s_setprio 0
	v_max3_f32 v174, v231, v66, v82
	s_nop 0
	v_max3_f32 v174, v174, v67, v83
	s_nop 0
	v_max3_f32 v174, v174, v68, v84
	s_nop 0
	v_max3_f32 v174, v174, v69, v85
	s_nop 0
	v_max3_f32 v174, v174, v70, v86
	s_nop 0
	v_max3_f32 v174, v174, v71, v87
	s_nop 0
	v_max3_f32 v174, v174, v72, v88
	s_nop 0
	v_max3_f32 v174, v174, v73, v89
	s_nop 0
	v_max3_f32 v174, v174, v74, v90
	s_nop 0
	v_max3_f32 v174, v174, v75, v91
	s_nop 0
	v_max3_f32 v174, v174, v76, v92
	s_nop 0
	v_max3_f32 v174, v174, v77, v93
	s_nop 0
	v_max3_f32 v174, v174, v78, v94
	s_nop 0
	v_max3_f32 v174, v174, v79, v95
	s_nop 0
	v_max3_f32 v174, v174, v80, v96
	s_nop 0
	v_max3_f32 v174, v174, v81, v97
	s_nop 0
	v_mov_b32_e32 v175, v174
	s_nop 1
	v_permlane32_swap_b32_e32 v174, v175
	v_max_f32_e32 v174, v174, v175
	v_cmp_gt_f32_e32 vcc, v174, v245
	s_cmp_eq_u64 vcc, 0
	s_cbranch_scc1 .Lsmf_2
	v_cndmask_b32_e32 v193, 0, v174, vcc
	v_mov_b32_e32 v175, 0x41000000
	v_cndmask_b32_e32 v245, v245, v175, vcc
	v_sub_f32_e32 v230, v230, v193
	v_max_f32_e32 v175, 0, v193
	v_exp_f32_e64 v204, -v175
	s_nop 0
	v_pk_mul_f32 v[64:65], v[64:65], v[204:205] op_sel_hi:[1,0]
	v_pk_mul_f32 v[62:63], v[62:63], v[204:205] op_sel_hi:[1,0]
	v_pk_mul_f32 v[60:61], v[60:61], v[204:205] op_sel_hi:[1,0]
	v_pk_mul_f32 v[58:59], v[58:59], v[204:205] op_sel_hi:[1,0]
	v_pk_mul_f32 v[56:57], v[56:57], v[204:205] op_sel_hi:[1,0]
	v_pk_mul_f32 v[54:55], v[54:55], v[204:205] op_sel_hi:[1,0]
	v_pk_mul_f32 v[52:53], v[52:53], v[204:205] op_sel_hi:[1,0]
	v_pk_mul_f32 v[50:51], v[50:51], v[204:205] op_sel_hi:[1,0]
	v_pk_mul_f32 v[48:49], v[48:49], v[204:205] op_sel_hi:[1,0]
	v_pk_mul_f32 v[46:47], v[46:47], v[204:205] op_sel_hi:[1,0]
	v_pk_mul_f32 v[44:45], v[44:45], v[204:205] op_sel_hi:[1,0]
	v_pk_mul_f32 v[42:43], v[42:43], v[204:205] op_sel_hi:[1,0]
	v_pk_mul_f32 v[40:41], v[40:41], v[204:205] op_sel_hi:[1,0]
	v_pk_mul_f32 v[38:39], v[38:39], v[204:205] op_sel_hi:[1,0]
	v_pk_mul_f32 v[36:37], v[36:37], v[204:205] op_sel_hi:[1,0]
	v_pk_mul_f32 v[34:35], v[34:35], v[204:205] op_sel_hi:[1,0]
	v_pk_mul_f32 v[32:33], v[32:33], v[204:205] op_sel_hi:[1,0]
	v_pk_mul_f32 v[30:31], v[30:31], v[204:205] op_sel_hi:[1,0]
	v_pk_mul_f32 v[28:29], v[28:29], v[204:205] op_sel_hi:[1,0]
	v_pk_mul_f32 v[26:27], v[26:27], v[204:205] op_sel_hi:[1,0]
	v_pk_mul_f32 v[24:25], v[24:25], v[204:205] op_sel_hi:[1,0]
	v_pk_mul_f32 v[22:23], v[22:23], v[204:205] op_sel_hi:[1,0]
	v_pk_mul_f32 v[20:21], v[20:21], v[204:205] op_sel_hi:[1,0]
	v_pk_mul_f32 v[18:19], v[18:19], v[204:205] op_sel_hi:[1,0]
	v_pk_mul_f32 v[16:17], v[16:17], v[204:205] op_sel_hi:[1,0]
	v_pk_mul_f32 v[14:15], v[14:15], v[204:205] op_sel_hi:[1,0]
	v_pk_mul_f32 v[12:13], v[12:13], v[204:205] op_sel_hi:[1,0]
	v_pk_mul_f32 v[10:11], v[10:11], v[204:205] op_sel_hi:[1,0]
	v_pk_mul_f32 v[8:9], v[8:9], v[204:205] op_sel_hi:[1,0]
	v_pk_mul_f32 v[6:7], v[6:7], v[204:205] op_sel_hi:[1,0]
	v_pk_mul_f32 v[4:5], v[4:5], v[204:205] op_sel_hi:[1,0]
	v_pk_mul_f32 v[2:3], v[2:3], v[204:205] op_sel_hi:[1,0]
.LBB0_92:
	v_pk_add_f32 v[66:67], v[66:67], v[192:193] op_sel:[0,1] op_sel_hi:[1,1] neg_lo:[0,1] neg_hi:[0,1]
	v_pk_add_f32 v[82:83], v[82:83], v[192:193] op_sel:[0,1] op_sel_hi:[1,1] neg_lo:[0,1] neg_hi:[0,1]
	v_exp_f32_e32 v66, v66
	v_exp_f32_e32 v67, v67
	v_exp_f32_e32 v82, v82
	v_exp_f32_e32 v83, v83
	v_pk_add_f32 v[68:69], v[68:69], v[192:193] op_sel:[0,1] op_sel_hi:[1,1] neg_lo:[0,1] neg_hi:[0,1]
	v_pk_add_f32 v[84:85], v[84:85], v[192:193] op_sel:[0,1] op_sel_hi:[1,1] neg_lo:[0,1] neg_hi:[0,1]
	v_exp_f32_e32 v68, v68
	v_exp_f32_e32 v69, v69
	v_exp_f32_e32 v84, v84
	v_exp_f32_e32 v85, v85
	v_pk_add_f32 v[174:175], v[66:67], v[82:83]
	v_pk_add_f32 v[70:71], v[70:71], v[192:193] op_sel:[0,1] op_sel_hi:[1,1] neg_lo:[0,1] neg_hi:[0,1]
	v_pk_add_f32 v[86:87], v[86:87], v[192:193] op_sel:[0,1] op_sel_hi:[1,1] neg_lo:[0,1] neg_hi:[0,1]
	v_exp_f32_e32 v70, v70
	v_exp_f32_e32 v71, v71
	v_exp_f32_e32 v86, v86
	v_exp_f32_e32 v87, v87
	v_pk_add_f32 v[174:175], v[174:175], v[68:69]
	v_pk_add_f32 v[174:175], v[174:175], v[84:85]
	v_pk_add_f32 v[72:73], v[72:73], v[192:193] op_sel:[0,1] op_sel_hi:[1,1] neg_lo:[0,1] neg_hi:[0,1]
	v_pk_add_f32 v[88:89], v[88:89], v[192:193] op_sel:[0,1] op_sel_hi:[1,1] neg_lo:[0,1] neg_hi:[0,1]
	v_exp_f32_e32 v72, v72
	v_exp_f32_e32 v73, v73
	v_exp_f32_e32 v88, v88
	v_exp_f32_e32 v89, v89
	v_pk_add_f32 v[174:175], v[174:175], v[70:71]
	v_pk_add_f32 v[174:175], v[174:175], v[86:87]
	v_pk_add_f32 v[74:75], v[74:75], v[192:193] op_sel:[0,1] op_sel_hi:[1,1] neg_lo:[0,1] neg_hi:[0,1]
	v_pk_add_f32 v[90:91], v[90:91], v[192:193] op_sel:[0,1] op_sel_hi:[1,1] neg_lo:[0,1] neg_hi:[0,1]
	v_exp_f32_e32 v74, v74
	v_exp_f32_e32 v75, v75
	v_exp_f32_e32 v90, v90
	v_exp_f32_e32 v91, v91
	v_pk_add_f32 v[174:175], v[174:175], v[72:73]
	v_pk_add_f32 v[174:175], v[174:175], v[88:89]
	v_pk_add_f32 v[76:77], v[76:77], v[192:193] op_sel:[0,1] op_sel_hi:[1,1] neg_lo:[0,1] neg_hi:[0,1]
	v_pk_add_f32 v[92:93], v[92:93], v[192:193] op_sel:[0,1] op_sel_hi:[1,1] neg_lo:[0,1] neg_hi:[0,1]
	v_exp_f32_e32 v76, v76
	v_exp_f32_e32 v77, v77
	v_exp_f32_e32 v92, v92
	v_exp_f32_e32 v93, v93
	v_pk_add_f32 v[174:175], v[174:175], v[74:75]
	v_pk_add_f32 v[174:175], v[174:175], v[90:91]
	v_pk_add_f32 v[78:79], v[78:79], v[192:193] op_sel:[0,1] op_sel_hi:[1,1] neg_lo:[0,1] neg_hi:[0,1]
	v_pk_add_f32 v[94:95], v[94:95], v[192:193] op_sel:[0,1] op_sel_hi:[1,1] neg_lo:[0,1] neg_hi:[0,1]
	v_exp_f32_e32 v78, v78
	v_exp_f32_e32 v79, v79
	v_exp_f32_e32 v94, v94
	v_exp_f32_e32 v95, v95
	v_pk_add_f32 v[174:175], v[174:175], v[76:77]
	v_pk_add_f32 v[174:175], v[174:175], v[92:93]
	v_pk_add_f32 v[80:81], v[80:81], v[192:193] op_sel:[0,1] op_sel_hi:[1,1] neg_lo:[0,1] neg_hi:[0,1]
	v_pk_add_f32 v[96:97], v[96:97], v[192:193] op_sel:[0,1] op_sel_hi:[1,1] neg_lo:[0,1] neg_hi:[0,1]
	v_exp_f32_e32 v80, v80
	v_exp_f32_e32 v81, v81
	v_exp_f32_e32 v96, v96
	v_exp_f32_e32 v97, v97
	v_pk_add_f32 v[174:175], v[174:175], v[78:79]
	v_pk_add_f32 v[174:175], v[174:175], v[94:95]
	s_nop 0
	v_pk_add_f32 v[174:175], v[174:175], v[80:81]
	v_pk_add_f32 v[174:175], v[174:175], v[96:97]
	v_add_f32_e32 v193, v174, v175
	s_branch .Lsmj_2
.Lsmf_2:
	v_mov_b32_e32 v204, 1.0
	v_exp_f32_e32 v66, v66
	v_exp_f32_e32 v67, v67
	v_exp_f32_e32 v82, v82
	v_exp_f32_e32 v83, v83
	v_exp_f32_e32 v68, v68
	v_exp_f32_e32 v69, v69
	v_exp_f32_e32 v84, v84
	v_exp_f32_e32 v85, v85
	v_pk_add_f32 v[174:175], v[66:67], v[82:83]
	v_exp_f32_e32 v70, v70
	v_exp_f32_e32 v71, v71
	v_exp_f32_e32 v86, v86
	v_exp_f32_e32 v87, v87
	v_pk_add_f32 v[174:175], v[174:175], v[68:69]
	v_pk_add_f32 v[174:175], v[174:175], v[84:85]
	v_exp_f32_e32 v72, v72
	v_exp_f32_e32 v73, v73
	v_exp_f32_e32 v88, v88
	v_exp_f32_e32 v89, v89
	v_pk_add_f32 v[174:175], v[174:175], v[70:71]
	v_pk_add_f32 v[174:175], v[174:175], v[86:87]
	v_exp_f32_e32 v74, v74
	v_exp_f32_e32 v75, v75
	v_exp_f32_e32 v90, v90
	v_exp_f32_e32 v91, v91
	v_pk_add_f32 v[174:175], v[174:175], v[72:73]
	v_pk_add_f32 v[174:175], v[174:175], v[88:89]
	v_exp_f32_e32 v76, v76
	v_exp_f32_e32 v77, v77
	v_exp_f32_e32 v92, v92
	v_exp_f32_e32 v93, v93
	v_pk_add_f32 v[174:175], v[174:175], v[74:75]
	v_pk_add_f32 v[174:175], v[174:175], v[90:91]
	v_exp_f32_e32 v78, v78
	v_exp_f32_e32 v79, v79
	v_exp_f32_e32 v94, v94
	v_exp_f32_e32 v95, v95
	v_pk_add_f32 v[174:175], v[174:175], v[76:77]
	v_pk_add_f32 v[174:175], v[174:175], v[92:93]
	v_exp_f32_e32 v80, v80
	v_exp_f32_e32 v81, v81
	v_exp_f32_e32 v96, v96
	v_exp_f32_e32 v97, v97
	v_pk_add_f32 v[174:175], v[174:175], v[78:79]
	v_pk_add_f32 v[174:175], v[174:175], v[94:95]
	s_nop 0
	v_pk_add_f32 v[174:175], v[174:175], v[80:81]
	v_pk_add_f32 v[174:175], v[174:175], v[96:97]
	v_add_f32_e32 v193, v174, v175
.Lsmj_2:
	v_fmac_f32_e32 v193, v216, v204
	v_add3_u32 v204, s30, v210, v211
	v_cvt_pk_bf16_f32 v174, v66, v67
	v_cvt_pk_bf16_f32 v175, v68, v69
	v_cvt_pk_bf16_f32 v176, v70, v71
	v_cvt_pk_bf16_f32 v177, v72, v73
	v_cvt_pk_bf16_f32 v216, v74, v75
	v_cvt_pk_bf16_f32 v217, v76, v77
	v_cvt_pk_bf16_f32 v218, v78, v79
	v_cvt_pk_bf16_f32 v219, v80, v81
	v_cvt_pk_bf16_f32 v220, v82, v83
	v_cvt_pk_bf16_f32 v221, v84, v85
	v_cvt_pk_bf16_f32 v222, v86, v87
	v_cvt_pk_bf16_f32 v223, v88, v89
	v_cvt_pk_bf16_f32 v224, v90, v91
	v_cvt_pk_bf16_f32 v225, v92, v93
	v_cvt_pk_bf16_f32 v226, v94, v95
	v_cvt_pk_bf16_f32 v227, v96, v97
	ds_read_b128 v[232:235], v204 offset:17408
	ds_read_b128 v[236:239], v204 offset:22016
	ds_read_b128 v[240:243], v204 offset:26624
	ds_read_b128 v[248:251], v204 offset:31232
	s_setprio 1
	s_waitcnt lgkmcnt(3)
	v_mfma_f32_32x32x16_bf16 v[50:65], v[232:235], v[174:177], v[50:65]
	s_waitcnt lgkmcnt(2)
	v_mfma_f32_32x32x16_bf16 v[34:49], v[236:239], v[174:177], v[34:49]
	s_waitcnt lgkmcnt(1)
	v_mfma_f32_32x32x16_bf16 v[18:33], v[240:243], v[174:177], v[18:33]
	s_waitcnt lgkmcnt(0)
	v_mfma_f32_32x32x16_bf16 v[2:17], v[248:251], v[174:177], v[2:17]
	s_setprio 0
	ds_read_b128 v[174:177], v204 offset:17440
	ds_read_b128 v[232:235], v204 offset:22048
	ds_read_b128 v[236:239], v204 offset:26656
	ds_read_b128 v[240:243], v204 offset:31264
	s_setprio 1
	s_waitcnt lgkmcnt(3)
	v_mfma_f32_32x32x16_bf16 v[50:65], v[174:177], v[216:219], v[50:65]
	s_waitcnt lgkmcnt(2)
	v_mfma_f32_32x32x16_bf16 v[34:49], v[232:235], v[216:219], v[34:49]
	s_waitcnt lgkmcnt(1)
	v_mfma_f32_32x32x16_bf16 v[18:33], v[236:239], v[216:219], v[18:33]
	s_waitcnt lgkmcnt(0)
	v_mfma_f32_32x32x16_bf16 v[2:17], v[240:243], v[216:219], v[2:17]
	s_setprio 0
	ds_read_b128 v[174:177], v204 offset:17472
	ds_read_b128 v[216:219], v204 offset:22080
	ds_read_b128 v[232:235], v204 offset:26688
	ds_read_b128 v[236:239], v204 offset:31296
	s_setprio 1
	s_waitcnt lgkmcnt(3)
	v_mfma_f32_32x32x16_bf16 v[50:65], v[174:177], v[220:223], v[50:65]
	s_waitcnt lgkmcnt(2)
	v_mfma_f32_32x32x16_bf16 v[34:49], v[216:219], v[220:223], v[34:49]
	s_waitcnt lgkmcnt(1)
	v_mfma_f32_32x32x16_bf16 v[18:33], v[232:235], v[220:223], v[18:33]
	s_waitcnt lgkmcnt(0)
	v_mfma_f32_32x32x16_bf16 v[2:17], v[236:239], v[220:223], v[2:17]
	s_setprio 0
	ds_read_b128 v[174:177], v204 offset:17504
	ds_read_b128 v[216:219], v204 offset:22112
	ds_read_b128 v[220:223], v204 offset:26720
	ds_read_b128 v[232:235], v204 offset:31328
	s_setprio 1
	s_waitcnt lgkmcnt(3)
	v_mfma_f32_32x32x16_bf16 v[50:65], v[174:177], v[224:227], v[50:65]
	s_waitcnt lgkmcnt(2)
	v_mfma_f32_32x32x16_bf16 v[34:49], v[216:219], v[224:227], v[34:49]
	s_waitcnt lgkmcnt(1)
	v_mfma_f32_32x32x16_bf16 v[18:33], v[220:223], v[224:227], v[18:33]
	s_waitcnt lgkmcnt(0)
	v_mfma_f32_32x32x16_bf16 v[2:17], v[232:235], v[224:227], v[2:17]
	s_setprio 0
	s_andn2_saveexec_b64 s[0:1], s[0:1]
	s_cbranch_execz .LBB0_87
.LBB0_93:
	v_max3_f32 v174, v231, v66, v82
	s_nop 0
	v_max3_f32 v174, v174, v67, v83
	s_nop 0
	v_max3_f32 v174, v174, v68, v84
	s_nop 0
	v_max3_f32 v174, v174, v69, v85
	s_nop 0
	v_max3_f32 v174, v174, v70, v86
	s_nop 0
	v_max3_f32 v174, v174, v71, v87
	s_nop 0
	v_max3_f32 v174, v174, v72, v88
	s_nop 0
	v_max3_f32 v174, v174, v73, v89
	s_nop 0
	v_max3_f32 v174, v174, v74, v90
	s_nop 0
	v_max3_f32 v174, v174, v75, v91
	s_nop 0
	v_max3_f32 v174, v174, v76, v92
	s_nop 0
	v_max3_f32 v174, v174, v77, v93
	s_nop 0
	v_max3_f32 v174, v174, v78, v94
	s_nop 0
	v_max3_f32 v174, v174, v79, v95
	s_nop 0
	v_max3_f32 v174, v174, v80, v96
	s_nop 0
	v_max3_f32 v174, v174, v81, v97
	s_nop 0
	v_mov_b32_e32 v175, v174
	s_nop 1
	v_permlane32_swap_b32_e32 v174, v175
	v_max_f32_e32 v174, v174, v175
	v_cmp_gt_f32_e32 vcc, v174, v245
	s_cmp_eq_u64 vcc, 0
	s_cbranch_scc1 .Lsmf_3
	v_cndmask_b32_e32 v193, 0, v174, vcc
	v_mov_b32_e32 v175, 0x41000000
	v_cndmask_b32_e32 v245, v245, v175, vcc
	v_sub_f32_e32 v230, v230, v193
	v_max_f32_e32 v175, 0, v193
	v_exp_f32_e64 v204, -v175
	s_nop 0
	v_pk_mul_f32 v[64:65], v[64:65], v[204:205] op_sel_hi:[1,0]
	v_pk_mul_f32 v[62:63], v[62:63], v[204:205] op_sel_hi:[1,0]
	v_pk_mul_f32 v[60:61], v[60:61], v[204:205] op_sel_hi:[1,0]
	v_pk_mul_f32 v[58:59], v[58:59], v[204:205] op_sel_hi:[1,0]
	v_pk_mul_f32 v[56:57], v[56:57], v[204:205] op_sel_hi:[1,0]
	v_pk_mul_f32 v[54:55], v[54:55], v[204:205] op_sel_hi:[1,0]
	v_pk_mul_f32 v[52:53], v[52:53], v[204:205] op_sel_hi:[1,0]
	v_pk_mul_f32 v[50:51], v[50:51], v[204:205] op_sel_hi:[1,0]
	v_pk_mul_f32 v[48:49], v[48:49], v[204:205] op_sel_hi:[1,0]
	v_pk_mul_f32 v[46:47], v[46:47], v[204:205] op_sel_hi:[1,0]
	v_pk_mul_f32 v[44:45], v[44:45], v[204:205] op_sel_hi:[1,0]
	v_pk_mul_f32 v[42:43], v[42:43], v[204:205] op_sel_hi:[1,0]
	v_pk_mul_f32 v[40:41], v[40:41], v[204:205] op_sel_hi:[1,0]
	v_pk_mul_f32 v[38:39], v[38:39], v[204:205] op_sel_hi:[1,0]
	v_pk_mul_f32 v[36:37], v[36:37], v[204:205] op_sel_hi:[1,0]
	v_pk_mul_f32 v[34:35], v[34:35], v[204:205] op_sel_hi:[1,0]
	v_pk_mul_f32 v[32:33], v[32:33], v[204:205] op_sel_hi:[1,0]
	v_pk_mul_f32 v[30:31], v[30:31], v[204:205] op_sel_hi:[1,0]
	v_pk_mul_f32 v[28:29], v[28:29], v[204:205] op_sel_hi:[1,0]
	v_pk_mul_f32 v[26:27], v[26:27], v[204:205] op_sel_hi:[1,0]
	v_pk_mul_f32 v[24:25], v[24:25], v[204:205] op_sel_hi:[1,0]
	v_pk_mul_f32 v[22:23], v[22:23], v[204:205] op_sel_hi:[1,0]
	v_pk_mul_f32 v[20:21], v[20:21], v[204:205] op_sel_hi:[1,0]
	v_pk_mul_f32 v[18:19], v[18:19], v[204:205] op_sel_hi:[1,0]
	v_pk_mul_f32 v[16:17], v[16:17], v[204:205] op_sel_hi:[1,0]
	v_pk_mul_f32 v[14:15], v[14:15], v[204:205] op_sel_hi:[1,0]
	v_pk_mul_f32 v[12:13], v[12:13], v[204:205] op_sel_hi:[1,0]
	v_pk_mul_f32 v[10:11], v[10:11], v[204:205] op_sel_hi:[1,0]
	v_pk_mul_f32 v[8:9], v[8:9], v[204:205] op_sel_hi:[1,0]
	v_pk_mul_f32 v[6:7], v[6:7], v[204:205] op_sel_hi:[1,0]
	v_pk_mul_f32 v[4:5], v[4:5], v[204:205] op_sel_hi:[1,0]
	v_pk_mul_f32 v[2:3], v[2:3], v[204:205] op_sel_hi:[1,0]

.Lsmj_3:
	v_add3_u32 v174, s47, v210, v211
	v_cvt_pk_bf16_f32 v66, v66, v67
	v_cvt_pk_bf16_f32 v67, v68, v69
	v_cvt_pk_bf16_f32 v68, v70, v71
	v_cvt_pk_bf16_f32 v69, v72, v73
	v_cvt_pk_bf16_f32 v70, v74, v75
	v_cvt_pk_bf16_f32 v71, v76, v77
	v_cvt_pk_bf16_f32 v72, v78, v79
	v_cvt_pk_bf16_f32 v73, v80, v81
	v_cvt_pk_bf16_f32 v74, v82, v83
	v_cvt_pk_bf16_f32 v75, v84, v85
	v_cvt_pk_bf16_f32 v76, v86, v87
	v_cvt_pk_bf16_f32 v77, v88, v89
	v_cvt_pk_bf16_f32 v78, v90, v91
	v_cvt_pk_bf16_f32 v79, v92, v93
	v_cvt_pk_bf16_f32 v80, v94, v95
	v_cvt_pk_bf16_f32 v81, v96, v97
	ds_read_b128 v[82:85], v174 offset:17408
	ds_read_b128 v[86:89], v174 offset:22016
	ds_read_b128 v[90:93], v174 offset:26624
	ds_read_b128 v[94:97], v174 offset:31232
	v_fmac_f32_e32 v193, v216, v204
	s_setprio 1
	s_waitcnt lgkmcnt(3)
	v_mfma_f32_32x32x16_bf16 v[50:65], v[82:85], v[66:69], v[50:65]
	s_waitcnt lgkmcnt(2)
	v_mfma_f32_32x32x16_bf16 v[34:49], v[86:89], v[66:69], v[34:49]
	s_waitcnt lgkmcnt(1)
	v_mfma_f32_32x32x16_bf16 v[18:33], v[90:93], v[66:69], v[18:33]
	s_waitcnt lgkmcnt(0)
	v_mfma_f32_32x32x16_bf16 v[2:17], v[94:97], v[66:69], v[2:17]
	s_setprio 0
	ds_read_b128 v[66:69], v174 offset:17440
	ds_read_b128 v[82:85], v174 offset:22048
	ds_read_b128 v[86:89], v174 offset:26656
	ds_read_b128 v[90:93], v174 offset:31264
	s_setprio 1
	s_waitcnt lgkmcnt(3)
	v_mfma_f32_32x32x16_bf16 v[50:65], v[66:69], v[70:73], v[50:65]
	s_waitcnt lgkmcnt(2)
	v_mfma_f32_32x32x16_bf16 v[34:49], v[82:85], v[70:73], v[34:49]
	s_waitcnt lgkmcnt(1)
	v_mfma_f32_32x32x16_bf16 v[18:33], v[86:89], v[70:73], v[18:33]
	s_waitcnt lgkmcnt(0)
	v_mfma_f32_32x32x16_bf16 v[2:17], v[90:93], v[70:73], v[2:17]
	s_setprio 0
	ds_read_b128 v[66:69], v174 offset:17472
	ds_read_b128 v[70:73], v174 offset:22080
	ds_read_b128 v[82:85], v174 offset:26688
	ds_read_b128 v[86:89], v174 offset:31296
	s_setprio 1
	s_waitcnt lgkmcnt(3)
	v_mfma_f32_32x32x16_bf16 v[50:65], v[66:69], v[74:77], v[50:65]
	s_waitcnt lgkmcnt(2)
	v_mfma_f32_32x32x16_bf16 v[34:49], v[70:73], v[74:77], v[34:49]
	s_waitcnt lgkmcnt(1)
	v_mfma_f32_32x32x16_bf16 v[18:33], v[82:85], v[74:77], v[18:33]
	s_waitcnt lgkmcnt(0)
	v_mfma_f32_32x32x16_bf16 v[2:17], v[86:89], v[74:77], v[2:17]
	s_setprio 0
	ds_read_b128 v[66:69], v174 offset:17504
	ds_read_b128 v[70:73], v174 offset:22112
	ds_read_b128 v[74:77], v174 offset:26720
	ds_read_b128 v[82:85], v174 offset:31328
	s_setprio 1
	s_waitcnt lgkmcnt(3)
	v_mfma_f32_32x32x16_bf16 v[50:65], v[66:69], v[78:81], v[50:65]
	s_waitcnt lgkmcnt(2)
	v_mfma_f32_32x32x16_bf16 v[34:49], v[70:73], v[78:81], v[34:49]
	s_waitcnt lgkmcnt(1)
	v_mfma_f32_32x32x16_bf16 v[18:33], v[74:77], v[78:81], v[18:33]
	s_waitcnt lgkmcnt(0)
	v_mfma_f32_32x32x16_bf16 v[2:17], v[82:85], v[78:81], v[2:17]
	s_setprio 0
	v_not_b32_e32 v66, v218
	v_not_b32_e32 v82, v205
	v_bfe_i32 v83, v66, 0, 1
	v_bfe_i32 v174, v82, 0, 1
	v_bfe_i32 v67, v66, 1, 1
	v_bfe_i32 v175, v82, 1, 1
	v_bfe_i32 v68, v66, 2, 1
	v_bfe_i32 v84, v82, 2, 1
	v_bfe_i32 v69, v66, 3, 1
	v_bfe_i32 v85, v82, 3, 1
	v_bfe_i32 v70, v66, 8, 1
	v_bfe_i32 v86, v82, 8, 1
	v_bfe_i32 v71, v66, 9, 1
	v_bfe_i32 v87, v82, 9, 1
	v_bfe_i32 v72, v66, 10, 1
	v_bfe_i32 v88, v82, 10, 1
	v_bfe_i32 v73, v66, 11, 1
	v_bfe_i32 v89, v82, 11, 1
	v_bfe_i32 v74, v66, 16, 1
	v_bfe_i32 v90, v82, 16, 1
	v_bfe_i32 v75, v66, 17, 1
	v_bfe_i32 v91, v82, 17, 1
	v_bfe_i32 v76, v66, 18, 1
	v_bfe_i32 v92, v82, 18, 1
	v_bfe_i32 v77, v66, 19, 1
	v_bfe_i32 v93, v82, 19, 1
	v_bfe_i32 v78, v66, 24, 1
	v_bfe_i32 v94, v82, 24, 1
	v_bfe_i32 v79, v66, 25, 1
	v_bfe_i32 v95, v82, 25, 1
	v_bfe_i32 v80, v66, 26, 1
	v_bfe_i32 v96, v82, 26, 1
	v_bfe_i32 v66, v66, 27, 1
	v_bfe_i32 v82, v82, 27, 1
	s_nop 0
	v_bfi_b32 v79, v79, v231, v230
	v_bfi_b32 v81, v66, v231, v230
	v_bfi_b32 v66, v83, v231, v230
	v_bfi_b32 v97, v82, v231, v230
	v_bfi_b32 v83, v175, v231, v230
	v_bfi_b32 v82, v174, v231, v230
	ds_read_b128 v[174:177], v217 offset:8704
	ds_read_b128 v[218:221], v217
	ds_read_b128 v[222:225], v217 offset:32
	ds_read_b128 v[226:229], v217 offset:8736
	ds_read_b128 v[232:235], v217 offset:64
	ds_read_b128 v[236:239], v217 offset:8768
	ds_read_b128 v[240:243], v217 offset:96
	ds_read_b128 v[248:251], v217 offset:8800
	v_bfi_b32 v80, v80, v231, v230
	v_bfi_b32 v78, v78, v231, v230
	v_bfi_b32 v77, v77, v231, v230
	v_bfi_b32 v76, v76, v231, v230
	v_bfi_b32 v75, v75, v231, v230
	v_bfi_b32 v74, v74, v231, v230
	v_bfi_b32 v73, v73, v231, v230
	v_bfi_b32 v72, v72, v231, v230
	v_bfi_b32 v71, v71, v231, v230
	v_bfi_b32 v70, v70, v231, v230
	v_bfi_b32 v69, v69, v231, v230
	v_bfi_b32 v68, v68, v231, v230
	v_bfi_b32 v67, v67, v231, v230
	v_bfi_b32 v96, v96, v231, v230
	v_bfi_b32 v95, v95, v231, v230
	v_bfi_b32 v94, v94, v231, v230
	v_bfi_b32 v93, v93, v231, v230
	v_bfi_b32 v92, v92, v231, v230
	v_bfi_b32 v91, v91, v231, v230
	v_bfi_b32 v90, v90, v231, v230
	v_bfi_b32 v89, v89, v231, v230
	v_bfi_b32 v88, v88, v231, v230
	v_bfi_b32 v87, v87, v231, v230
	v_bfi_b32 v86, v86, v231, v230
	v_bfi_b32 v85, v85, v231, v230
	v_bfi_b32 v84, v84, v231, v230
	s_setprio 1
	s_waitcnt lgkmcnt(6)
	v_mfma_f32_32x32x16_bf16 v[66:81], v[218:221], v[98:101], v[66:81]
	v_mfma_f32_32x32x16_bf16 v[82:97], v[174:177], v[98:101], v[82:97]
	s_waitcnt lgkmcnt(5)
	v_mfma_f32_32x32x16_bf16 v[66:81], v[222:225], v[102:105], v[66:81]
	s_waitcnt lgkmcnt(4)
	v_mfma_f32_32x32x16_bf16 v[82:97], v[226:229], v[102:105], v[82:97]
	s_waitcnt lgkmcnt(3)
	v_mfma_f32_32x32x16_bf16 v[66:81], v[232:235], v[106:109], v[66:81]
	s_waitcnt lgkmcnt(2)
	v_mfma_f32_32x32x16_bf16 v[82:97], v[236:239], v[106:109], v[82:97]
	s_waitcnt lgkmcnt(1)
	v_mfma_f32_32x32x16_bf16 v[66:81], v[240:243], v[110:113], v[66:81]
	s_waitcnt lgkmcnt(0)
	v_mfma_f32_32x32x16_bf16 v[82:97], v[248:251], v[110:113], v[82:97]
	s_setprio 0
	ds_read_b128 v[174:177], v217 offset:128
	ds_read_b128 v[218:221], v217 offset:160
	ds_read_b128 v[222:225], v217 offset:8832
	ds_read_b128 v[226:229], v217 offset:8864
	ds_read_b128 v[232:235], v217 offset:192
	ds_read_b128 v[236:239], v217 offset:224
	ds_read_b128 v[240:243], v217 offset:8896
	ds_read_b128 v[248:251], v217 offset:8928
	s_setprio 1
	s_waitcnt lgkmcnt(7)
	v_mfma_f32_32x32x16_bf16 v[66:81], v[174:177], v[114:117], v[66:81]
	s_waitcnt lgkmcnt(5)
	v_mfma_f32_32x32x16_bf16 v[82:97], v[222:225], v[114:117], v[82:97]
	v_mfma_f32_32x32x16_bf16 v[66:81], v[218:221], v[118:121], v[66:81]
	s_waitcnt lgkmcnt(4)
	v_mfma_f32_32x32x16_bf16 v[82:97], v[226:229], v[118:121], v[82:97]
	s_waitcnt lgkmcnt(3)
	v_mfma_f32_32x32x16_bf16 v[66:81], v[232:235], v[122:125], v[66:81]
	s_waitcnt lgkmcnt(1)
	v_mfma_f32_32x32x16_bf16 v[82:97], v[240:243], v[122:125], v[82:97]
	v_mfma_f32_32x32x16_bf16 v[66:81], v[236:239], v[126:129], v[66:81]
	s_waitcnt lgkmcnt(0)
	v_mfma_f32_32x32x16_bf16 v[82:97], v[248:251], v[126:129], v[82:97]
	s_setprio 0
	s_or_b64 exec, exec, s[0:1]
	s_and_b64 vcc, exec, s[8:9]
	s_cbranch_vccz .LBB0_88
	s_branch .LBB0_89
.LBB0_96:
	s_and_saveexec_b64 s[0:1], s[4:5]
	s_cbranch_execz .LBB0_57
	v_max3_f32 v98, v231, v66, v82
	s_nop 0
	v_max3_f32 v98, v98, v67, v83
	s_nop 0
	v_max3_f32 v98, v98, v68, v84
	s_nop 0
	v_max3_f32 v98, v98, v69, v85
	s_nop 0
	v_max3_f32 v98, v98, v70, v86
	s_nop 0
	v_max3_f32 v98, v98, v71, v87
	s_nop 0
	v_max3_f32 v98, v98, v72, v88
	s_nop 0
	v_max3_f32 v98, v98, v73, v89
	s_nop 0
	v_max3_f32 v98, v98, v74, v90
	s_nop 0
	v_max3_f32 v98, v98, v75, v91
	s_nop 0
	v_max3_f32 v98, v98, v76, v92
	s_nop 0
	v_max3_f32 v98, v98, v77, v93
	s_nop 0
	v_max3_f32 v98, v98, v78, v94
	s_nop 0
	v_max3_f32 v98, v98, v79, v95
	s_nop 0
	v_max3_f32 v98, v98, v80, v96
	s_nop 0
	v_max3_f32 v98, v98, v81, v97
	s_nop 0
	v_mov_b32_e32 v99, v98
	s_nop 1
	v_permlane32_swap_b32_e32 v98, v99
	v_max_f32_e32 v98, v98, v99
	v_cmp_gt_f32_e32 vcc, v98, v245
	s_cmp_eq_u64 vcc, 0
	s_cbranch_scc1 .Lsmf_4
	v_cndmask_b32_e32 v99, 0, v98, vcc
	v_mov_b32_e32 v102, 0x41000000
	v_cndmask_b32_e32 v245, v245, v102, vcc
	v_sub_f32_e32 v230, v230, v99
	v_max_f32_e32 v102, 0, v99
	v_exp_f32_e64 v98, -v102
	s_nop 0
	v_pk_mul_f32 v[64:65], v[64:65], v[98:99] op_sel_hi:[1,0]
	v_pk_mul_f32 v[62:63], v[62:63], v[98:99] op_sel_hi:[1,0]
	v_pk_mul_f32 v[60:61], v[60:61], v[98:99] op_sel_hi:[1,0]
	v_pk_mul_f32 v[58:59], v[58:59], v[98:99] op_sel_hi:[1,0]
	v_pk_mul_f32 v[56:57], v[56:57], v[98:99] op_sel_hi:[1,0]
	v_pk_mul_f32 v[54:55], v[54:55], v[98:99] op_sel_hi:[1,0]
	v_pk_mul_f32 v[52:53], v[52:53], v[98:99] op_sel_hi:[1,0]
	v_pk_mul_f32 v[50:51], v[50:51], v[98:99] op_sel_hi:[1,0]
	v_pk_mul_f32 v[48:49], v[48:49], v[98:99] op_sel_hi:[1,0]
	v_pk_mul_f32 v[46:47], v[46:47], v[98:99] op_sel_hi:[1,0]
	v_pk_mul_f32 v[44:45], v[44:45], v[98:99] op_sel_hi:[1,0]
	v_pk_mul_f32 v[42:43], v[42:43], v[98:99] op_sel_hi:[1,0]
	v_pk_mul_f32 v[40:41], v[40:41], v[98:99] op_sel_hi:[1,0]
	v_pk_mul_f32 v[38:39], v[38:39], v[98:99] op_sel_hi:[1,0]
	v_pk_mul_f32 v[36:37], v[36:37], v[98:99] op_sel_hi:[1,0]
	v_pk_mul_f32 v[34:35], v[34:35], v[98:99] op_sel_hi:[1,0]
	v_pk_mul_f32 v[32:33], v[32:33], v[98:99] op_sel_hi:[1,0]
	v_pk_mul_f32 v[30:31], v[30:31], v[98:99] op_sel_hi:[1,0]
	v_pk_mul_f32 v[28:29], v[28:29], v[98:99] op_sel_hi:[1,0]
	v_pk_mul_f32 v[26:27], v[26:27], v[98:99] op_sel_hi:[1,0]
	v_pk_mul_f32 v[24:25], v[24:25], v[98:99] op_sel_hi:[1,0]
	v_pk_mul_f32 v[22:23], v[22:23], v[98:99] op_sel_hi:[1,0]
	v_pk_mul_f32 v[20:21], v[20:21], v[98:99] op_sel_hi:[1,0]
	v_pk_mul_f32 v[18:19], v[18:19], v[98:99] op_sel_hi:[1,0]
	v_pk_mul_f32 v[16:17], v[16:17], v[98:99] op_sel_hi:[1,0]
	v_pk_mul_f32 v[14:15], v[14:15], v[98:99] op_sel_hi:[1,0]
	v_pk_mul_f32 v[12:13], v[12:13], v[98:99] op_sel_hi:[1,0]
	v_pk_mul_f32 v[10:11], v[10:11], v[98:99] op_sel_hi:[1,0]
	v_pk_mul_f32 v[8:9], v[8:9], v[98:99] op_sel_hi:[1,0]
	v_pk_mul_f32 v[6:7], v[6:7], v[98:99] op_sel_hi:[1,0]
	v_pk_mul_f32 v[4:5], v[4:5], v[98:99] op_sel_hi:[1,0]
	v_pk_mul_f32 v[2:3], v[2:3], v[98:99] op_sel_hi:[1,0]
	s_branch .LBB0_56
.Lsmf_4:
	v_mov_b32_e32 v98, 1.0
	s_branch .Lsmg_4
